# attention: packed f32 softmax adds, 8 dwordx4 output stores per lane via v_permlane32_swap instead of 16 dwordx2; GEMM tile loop: dropped the redundant first accumulator clear (9 loops)
# speedup vs baseline: 1.0092x; 1.0092x over previous
.LBB0_251:
	s_ashr_i32 s49, s48, 31
	s_lshl_b64 s[18:19], s[48:49], 19
	s_add_u32 s50, s17, s18
	s_addc_u32 s51, s21, s19
	s_ashr_i32 s47, s46, 31
	s_lshl_b64 s[18:19], s[46:47], 19
	s_add_u32 s54, s22, s18
	v_mov_b32_e32 v129, 0
	s_addc_u32 s55, s23, s19
	s_andn2_b64 vcc, exec, s[34:35]
	s_cbranch_vccnz .LBB0_255
	s_and_b64 s[18:19], s[42:43], exec
	s_cselect_b32 s47, s51, s57
	s_cselect_b32 s49, s50, s56
	s_cselect_b32 s72, s55, s27
	s_cselect_b32 s73, s54, s26
	s_add_u32 s78, s56, 0x100
	s_addc_u32 s79, s57, 0
	s_add_u32 s80, s26, 0x100
	v_mov_b32_e32 v2, 0
	s_addc_u32 s81, s27, 0
	s_mov_b32 s18, 0
	v_mov_b32_e32 v3, v2
	v_mov_b32_e32 v4, v2
	v_mov_b32_e32 v5, v2
	v_mov_b32_e32 v6, v2
	v_mov_b32_e32 v7, v2
	v_mov_b32_e32 v8, v2
	v_mov_b32_e32 v9, v2
	v_mov_b32_e32 v18, v2
	v_mov_b32_e32 v19, v2
	v_mov_b32_e32 v20, v2
	v_mov_b32_e32 v21, v2
	v_mov_b32_e32 v22, v2
	v_mov_b32_e32 v23, v2
	v_mov_b32_e32 v24, v2
	v_mov_b32_e32 v25, v2
	v_mov_b32_e32 v34, v2
	v_mov_b32_e32 v35, v2
	v_mov_b32_e32 v36, v2
	v_mov_b32_e32 v37, v2
	v_mov_b32_e32 v38, v2
	v_mov_b32_e32 v39, v2
	v_mov_b32_e32 v40, v2
	v_mov_b32_e32 v41, v2
	v_mov_b32_e32 v50, v2
	v_mov_b32_e32 v51, v2
	v_mov_b32_e32 v52, v2
	v_mov_b32_e32 v53, v2
	v_mov_b32_e32 v54, v2
	v_mov_b32_e32 v55, v2
	v_mov_b32_e32 v56, v2
	v_mov_b32_e32 v57, v2
	v_mov_b32_e32 v10, v2
	v_mov_b32_e32 v11, v2
	v_mov_b32_e32 v12, v2
	v_mov_b32_e32 v13, v2
	v_mov_b32_e32 v14, v2
	v_mov_b32_e32 v15, v2
	v_mov_b32_e32 v16, v2
	v_mov_b32_e32 v17, v2
	v_mov_b32_e32 v26, v2
	v_mov_b32_e32 v27, v2
	v_mov_b32_e32 v28, v2
	v_mov_b32_e32 v29, v2
	v_mov_b32_e32 v30, v2
	v_mov_b32_e32 v31, v2
	v_mov_b32_e32 v32, v2
	v_mov_b32_e32 v33, v2
	v_mov_b32_e32 v42, v2
	v_mov_b32_e32 v43, v2
	v_mov_b32_e32 v44, v2
	v_mov_b32_e32 v45, v2
	v_mov_b32_e32 v46, v2
	v_mov_b32_e32 v47, v2
	v_mov_b32_e32 v48, v2
	v_mov_b32_e32 v49, v2
	v_mov_b32_e32 v58, v2
	v_mov_b32_e32 v59, v2
	v_mov_b32_e32 v60, v2
	v_mov_b32_e32 v61, v2
	v_mov_b32_e32 v62, v2
	v_mov_b32_e32 v63, v2
	v_mov_b32_e32 v64, v2
	v_mov_b32_e32 v65, v2
	v_mov_b32_e32 v66, v2
	v_mov_b32_e32 v67, v2
	v_mov_b32_e32 v68, v2
	v_mov_b32_e32 v69, v2
	v_mov_b32_e32 v70, v2
	v_mov_b32_e32 v71, v2
	v_mov_b32_e32 v72, v2
	v_mov_b32_e32 v73, v2
	v_mov_b32_e32 v82, v2
	v_mov_b32_e32 v83, v2
	v_mov_b32_e32 v84, v2
	v_mov_b32_e32 v85, v2
	v_mov_b32_e32 v86, v2
	v_mov_b32_e32 v87, v2
	v_mov_b32_e32 v88, v2
	v_mov_b32_e32 v89, v2
	v_mov_b32_e32 v98, v2
	v_mov_b32_e32 v99, v2
	v_mov_b32_e32 v100, v2
	v_mov_b32_e32 v101, v2
	v_mov_b32_e32 v102, v2
	v_mov_b32_e32 v103, v2
	v_mov_b32_e32 v104, v2
	v_mov_b32_e32 v105, v2
	v_mov_b32_e32 v114, v2
	v_mov_b32_e32 v115, v2
	v_mov_b32_e32 v116, v2
	v_mov_b32_e32 v117, v2
	v_mov_b32_e32 v118, v2
	v_mov_b32_e32 v119, v2
	v_mov_b32_e32 v120, v2
	v_mov_b32_e32 v121, v2
	v_mov_b32_e32 v74, v2
	v_mov_b32_e32 v75, v2
	v_mov_b32_e32 v76, v2
	v_mov_b32_e32 v77, v2
	v_mov_b32_e32 v78, v2
	v_mov_b32_e32 v79, v2
	v_mov_b32_e32 v80, v2
	v_mov_b32_e32 v81, v2
	v_mov_b32_e32 v90, v2
	v_mov_b32_e32 v91, v2
	v_mov_b32_e32 v92, v2
	v_mov_b32_e32 v93, v2
	v_mov_b32_e32 v94, v2
	v_mov_b32_e32 v95, v2
	v_mov_b32_e32 v96, v2
	v_mov_b32_e32 v97, v2
	v_mov_b32_e32 v106, v2
	v_mov_b32_e32 v107, v2
	v_mov_b32_e32 v108, v2
	v_mov_b32_e32 v109, v2
	v_mov_b32_e32 v110, v2
	v_mov_b32_e32 v111, v2
	v_mov_b32_e32 v112, v2
	v_mov_b32_e32 v113, v2
	v_mov_b32_e32 v122, v2
	v_mov_b32_e32 v123, v2
	v_mov_b32_e32 v124, v2
	v_mov_b32_e32 v125, v2
	v_mov_b32_e32 v126, v2
	v_mov_b32_e32 v127, v2
	v_mov_b32_e32 v128, v2
	v_mov_b32_e32 v129, v2

.LBB0_438:
	s_ashr_i32 s61, s60, 31
	s_lshl_b64 s[18:19], s[60:61], 18
	s_add_u32 s62, s17, s18
	s_addc_u32 s63, s21, s19
	s_ashr_i32 s55, s54, 31
	s_lshl_b64 s[18:19], s[54:55], 18
	s_add_u32 s36, s22, s18
	v_mov_b32_e32 v129, 0
	s_addc_u32 s37, s23, s19
	s_andn2_b64 vcc, exec, s[30:31]
	s_cbranch_vccnz .LBB0_442
	s_and_b64 s[18:19], s[42:43], exec
	s_cselect_b32 s1, s63, s45
	s_cselect_b32 s3, s62, s44
	s_cselect_b32 s40, s37, s27
	s_cselect_b32 s41, s36, s26
	s_add_u32 s55, s44, 0x100
	s_addc_u32 s61, s45, 0
	s_add_u32 s80, s26, 0x100
	v_mov_b32_e32 v2, 0
	s_addc_u32 s81, s27, 0
	s_mov_b32 s18, 0
	v_mov_b32_e32 v3, v2
	v_mov_b32_e32 v4, v2
	v_mov_b32_e32 v5, v2
	v_mov_b32_e32 v6, v2
	v_mov_b32_e32 v7, v2
	v_mov_b32_e32 v8, v2
	v_mov_b32_e32 v9, v2
	v_mov_b32_e32 v10, v2
	v_mov_b32_e32 v11, v2
	v_mov_b32_e32 v12, v2
	v_mov_b32_e32 v13, v2
	v_mov_b32_e32 v14, v2
	v_mov_b32_e32 v15, v2
	v_mov_b32_e32 v16, v2
	v_mov_b32_e32 v17, v2
	v_mov_b32_e32 v18, v2
	v_mov_b32_e32 v19, v2
	v_mov_b32_e32 v20, v2
	v_mov_b32_e32 v21, v2
	v_mov_b32_e32 v22, v2
	v_mov_b32_e32 v23, v2
	v_mov_b32_e32 v24, v2
	v_mov_b32_e32 v25, v2
	v_mov_b32_e32 v26, v2
	v_mov_b32_e32 v27, v2
	v_mov_b32_e32 v28, v2
	v_mov_b32_e32 v29, v2
	v_mov_b32_e32 v30, v2
	v_mov_b32_e32 v31, v2
	v_mov_b32_e32 v32, v2
	v_mov_b32_e32 v33, v2
	v_mov_b32_e32 v66, v2
	v_mov_b32_e32 v67, v2
	v_mov_b32_e32 v68, v2
	v_mov_b32_e32 v69, v2
	v_mov_b32_e32 v70, v2
	v_mov_b32_e32 v71, v2
	v_mov_b32_e32 v72, v2
	v_mov_b32_e32 v73, v2
	v_mov_b32_e32 v74, v2
	v_mov_b32_e32 v75, v2
	v_mov_b32_e32 v76, v2
	v_mov_b32_e32 v77, v2
	v_mov_b32_e32 v78, v2
	v_mov_b32_e32 v79, v2
	v_mov_b32_e32 v80, v2
	v_mov_b32_e32 v81, v2
	v_mov_b32_e32 v82, v2
	v_mov_b32_e32 v83, v2
	v_mov_b32_e32 v84, v2
	v_mov_b32_e32 v85, v2
	v_mov_b32_e32 v86, v2
	v_mov_b32_e32 v87, v2
	v_mov_b32_e32 v88, v2
	v_mov_b32_e32 v89, v2
	v_mov_b32_e32 v90, v2
	v_mov_b32_e32 v91, v2
	v_mov_b32_e32 v92, v2
	v_mov_b32_e32 v93, v2
	v_mov_b32_e32 v94, v2
	v_mov_b32_e32 v95, v2
	v_mov_b32_e32 v96, v2
	v_mov_b32_e32 v97, v2
	v_mov_b32_e32 v34, v2
	v_mov_b32_e32 v35, v2
	v_mov_b32_e32 v36, v2
	v_mov_b32_e32 v37, v2
	v_mov_b32_e32 v38, v2
	v_mov_b32_e32 v39, v2
	v_mov_b32_e32 v40, v2
	v_mov_b32_e32 v41, v2
	v_mov_b32_e32 v42, v2
	v_mov_b32_e32 v43, v2
	v_mov_b32_e32 v44, v2
	v_mov_b32_e32 v45, v2
	v_mov_b32_e32 v46, v2
	v_mov_b32_e32 v47, v2
	v_mov_b32_e32 v48, v2
	v_mov_b32_e32 v49, v2
	v_mov_b32_e32 v50, v2
	v_mov_b32_e32 v51, v2
	v_mov_b32_e32 v52, v2
	v_mov_b32_e32 v53, v2
	v_mov_b32_e32 v54, v2
	v_mov_b32_e32 v55, v2
	v_mov_b32_e32 v56, v2
	v_mov_b32_e32 v57, v2
	v_mov_b32_e32 v58, v2
	v_mov_b32_e32 v59, v2
	v_mov_b32_e32 v60, v2
	v_mov_b32_e32 v61, v2
	v_mov_b32_e32 v62, v2
	v_mov_b32_e32 v63, v2
	v_mov_b32_e32 v64, v2
	v_mov_b32_e32 v65, v2
	v_mov_b32_e32 v98, v2
	v_mov_b32_e32 v99, v2
	v_mov_b32_e32 v100, v2
	v_mov_b32_e32 v101, v2
	v_mov_b32_e32 v102, v2
	v_mov_b32_e32 v103, v2
	v_mov_b32_e32 v104, v2
	v_mov_b32_e32 v105, v2
	v_mov_b32_e32 v106, v2
	v_mov_b32_e32 v107, v2
	v_mov_b32_e32 v108, v2
	v_mov_b32_e32 v109, v2
	v_mov_b32_e32 v110, v2
	v_mov_b32_e32 v111, v2
	v_mov_b32_e32 v112, v2
	v_mov_b32_e32 v113, v2
	v_mov_b32_e32 v114, v2
	v_mov_b32_e32 v115, v2
	v_mov_b32_e32 v116, v2
	v_mov_b32_e32 v117, v2
	v_mov_b32_e32 v118, v2
	v_mov_b32_e32 v119, v2
	v_mov_b32_e32 v120, v2
	v_mov_b32_e32 v121, v2
	v_mov_b32_e32 v122, v2
	v_mov_b32_e32 v123, v2
	v_mov_b32_e32 v124, v2
	v_mov_b32_e32 v125, v2
	v_mov_b32_e32 v126, v2
	v_mov_b32_e32 v127, v2
	v_mov_b32_e32 v128, v2
	v_mov_b32_e32 v129, v2

.LBB0_510:
	s_ashr_i32 s55, s54, 31
	s_lshl_b64 s[18:19], s[54:55], 17
	s_cmp_eq_u32 s70, 0
	s_cselect_b32 s55, s30, s2
	s_cselect_b32 s51, s31, s3
	s_cselect_b32 s61, s1, s31
	s_cselect_b32 s60, s0, s30
	s_add_u32 s56, s55, s18
	s_addc_u32 s57, s51, s19
	s_ashr_i32 s51, s50, 31
	s_lshl_b64 s[18:19], s[50:51], 17
	s_add_u32 s60, s60, s18
	v_mov_b32_e32 v125, 0
	s_addc_u32 s61, s61, s19
	s_andn2_b64 vcc, exec, s[36:37]
	s_cbranch_vccnz .LBB0_514
	s_and_b64 s[18:19], s[42:43], exec
	s_cselect_b32 s51, s57, s63
	s_cselect_b32 s55, s56, s62
	s_cselect_b32 s72, s61, s27
	s_cselect_b32 s73, s60, s26
	s_add_u32 s78, s62, 0x100
	s_addc_u32 s79, s63, 0
	s_add_u32 s80, s26, 0x100
	v_mov_b32_e32 v2, 0
	s_addc_u32 s81, s27, 0
	s_mov_b32 s18, 0
	v_mov_b32_e32 v3, v2
	v_mov_b32_e32 v4, v2
	v_mov_b32_e32 v5, v2
	v_mov_b32_e32 v6, v2
	v_mov_b32_e32 v7, v2
	v_mov_b32_e32 v8, v2
	v_mov_b32_e32 v9, v2
	v_mov_b32_e32 v18, v2
	v_mov_b32_e32 v19, v2
	v_mov_b32_e32 v20, v2
	v_mov_b32_e32 v21, v2
	v_mov_b32_e32 v22, v2
	v_mov_b32_e32 v23, v2
	v_mov_b32_e32 v24, v2
	v_mov_b32_e32 v25, v2
	v_mov_b32_e32 v34, v2
	v_mov_b32_e32 v35, v2
	v_mov_b32_e32 v36, v2
	v_mov_b32_e32 v37, v2
	v_mov_b32_e32 v38, v2
	v_mov_b32_e32 v39, v2
	v_mov_b32_e32 v40, v2
	v_mov_b32_e32 v41, v2
	v_mov_b32_e32 v50, v2
	v_mov_b32_e32 v51, v2
	v_mov_b32_e32 v52, v2
	v_mov_b32_e32 v53, v2
	v_mov_b32_e32 v54, v2
	v_mov_b32_e32 v55, v2
	v_mov_b32_e32 v56, v2
	v_mov_b32_e32 v57, v2
	v_mov_b32_e32 v10, v2
	v_mov_b32_e32 v11, v2
	v_mov_b32_e32 v12, v2
	v_mov_b32_e32 v13, v2
	v_mov_b32_e32 v14, v2
	v_mov_b32_e32 v15, v2
	v_mov_b32_e32 v16, v2
	v_mov_b32_e32 v17, v2
	v_mov_b32_e32 v26, v2
	v_mov_b32_e32 v27, v2
	v_mov_b32_e32 v28, v2
	v_mov_b32_e32 v29, v2
	v_mov_b32_e32 v30, v2
	v_mov_b32_e32 v31, v2
	v_mov_b32_e32 v32, v2
	v_mov_b32_e32 v33, v2
	v_mov_b32_e32 v42, v2
	v_mov_b32_e32 v43, v2
	v_mov_b32_e32 v44, v2
	v_mov_b32_e32 v45, v2
	v_mov_b32_e32 v46, v2
	v_mov_b32_e32 v47, v2
	v_mov_b32_e32 v48, v2
	v_mov_b32_e32 v49, v2
	v_mov_b32_e32 v58, v2
	v_mov_b32_e32 v59, v2
	v_mov_b32_e32 v60, v2
	v_mov_b32_e32 v61, v2
	v_mov_b32_e32 v62, v2
	v_mov_b32_e32 v63, v2
	v_mov_b32_e32 v64, v2
	v_mov_b32_e32 v65, v2
	v_mov_b32_e32 v66, v2
	v_mov_b32_e32 v67, v2
	v_mov_b32_e32 v68, v2
	v_mov_b32_e32 v69, v2
	v_mov_b32_e32 v70, v2
	v_mov_b32_e32 v71, v2
	v_mov_b32_e32 v72, v2
	v_mov_b32_e32 v73, v2
	v_mov_b32_e32 v82, v2
	v_mov_b32_e32 v83, v2
	v_mov_b32_e32 v84, v2
	v_mov_b32_e32 v85, v2
	v_mov_b32_e32 v86, v2
	v_mov_b32_e32 v87, v2
	v_mov_b32_e32 v88, v2
	v_mov_b32_e32 v89, v2
	v_mov_b32_e32 v98, v2
	v_mov_b32_e32 v99, v2
	v_mov_b32_e32 v100, v2
	v_mov_b32_e32 v101, v2
	v_mov_b32_e32 v102, v2
	v_mov_b32_e32 v103, v2
	v_mov_b32_e32 v104, v2
	v_mov_b32_e32 v105, v2
	v_mov_b32_e32 v114, v2
	v_mov_b32_e32 v115, v2
	v_mov_b32_e32 v116, v2
	v_mov_b32_e32 v117, v2
	v_mov_b32_e32 v118, v2
	v_mov_b32_e32 v119, v2
	v_mov_b32_e32 v120, v2
	v_mov_b32_e32 v121, v2
	v_mov_b32_e32 v74, v2
	v_mov_b32_e32 v75, v2
	v_mov_b32_e32 v76, v2
	v_mov_b32_e32 v77, v2
	v_mov_b32_e32 v78, v2
	v_mov_b32_e32 v79, v2
	v_mov_b32_e32 v80, v2
	v_mov_b32_e32 v81, v2
	v_mov_b32_e32 v90, v2
	v_mov_b32_e32 v91, v2
	v_mov_b32_e32 v92, v2
	v_mov_b32_e32 v93, v2
	v_mov_b32_e32 v94, v2
	v_mov_b32_e32 v95, v2
	v_mov_b32_e32 v96, v2
	v_mov_b32_e32 v97, v2
	v_mov_b32_e32 v106, v2
	v_mov_b32_e32 v107, v2
	v_mov_b32_e32 v108, v2
	v_mov_b32_e32 v109, v2
	v_mov_b32_e32 v110, v2
	v_mov_b32_e32 v111, v2
	v_mov_b32_e32 v112, v2
	v_mov_b32_e32 v113, v2
	v_mov_b32_e32 v126, v2
	v_mov_b32_e32 v127, v2
	v_mov_b32_e32 v128, v2
	v_mov_b32_e32 v129, v2
	v_mov_b32_e32 v122, v2
	v_mov_b32_e32 v123, v2
	v_mov_b32_e32 v124, v2
	v_mov_b32_e32 v125, v2

.LBB0_591:
	v_sub_f32_e32 v2, v80, v4
	v_sub_f32_e32 v5, v96, v4
	v_exp_f32_e32 v2, v2
	v_exp_f32_e32 v5, v5
	v_sub_f32_e32 v7, v81, v4
	v_sub_f32_e32 v8, v97, v4
	v_exp_f32_e32 v7, v7
	v_exp_f32_e32 v10, v8
	v_add_f32_e32 v6, v2, v5
	v_add_f32_e32 v6, 0, v6
	v_sub_f32_e32 v9, v98, v4
	v_add_f32_e32 v8, v7, v10
	v_add_f32_e32 v6, v8, v6
	v_sub_f32_e32 v8, v82, v4
	v_exp_f32_e32 v8, v8
	v_exp_f32_e32 v11, v9
	v_sub_f32_e32 v12, v99, v4
	v_exp_f32_e32 v12, v12
	v_sub_f32_e32 v15, v100, v4
	v_add_f32_e32 v9, v8, v11
	v_add_f32_e32 v6, v9, v6
	v_sub_f32_e32 v9, v83, v4
	v_exp_f32_e32 v9, v9
	v_exp_f32_e32 v15, v15
	v_sub_f32_e32 v81, v101, v4
	v_exp_f32_e32 v81, v81
	v_add_f32_e32 v13, v9, v12
	v_add_f32_e32 v6, v13, v6
	v_sub_f32_e32 v13, v84, v4
	v_exp_f32_e32 v13, v13
	v_sub_f32_e32 v83, v102, v4
	v_exp_f32_e32 v83, v83
	v_sub_f32_e32 v90, v90, v4
	v_add_f32_e32 v80, v13, v15
	v_add_f32_e32 v6, v80, v6
	v_sub_f32_e32 v80, v85, v4
	v_exp_f32_e32 v80, v80
	v_sub_f32_e32 v85, v103, v4
	v_exp_f32_e32 v85, v85
	v_exp_f32_e32 v90, v90
	v_add_f32_e32 v82, v80, v81
	v_add_f32_e32 v6, v82, v6
	v_sub_f32_e32 v82, v86, v4
	v_exp_f32_e32 v82, v82
	v_sub_f32_e32 v91, v91, v4
	v_exp_f32_e32 v91, v91
	v_sub_f32_e32 v92, v92, v4
	v_add_f32_e32 v84, v82, v83
	v_add_f32_e32 v6, v84, v6
	v_sub_f32_e32 v84, v87, v4
	v_exp_f32_e32 v84, v84
	v_sub_f32_e32 v87, v104, v4
	v_exp_f32_e32 v87, v87
	v_exp_f32_e32 v92, v92
	v_add_f32_e32 v86, v84, v85
	v_add_f32_e32 v6, v86, v6
	v_sub_f32_e32 v86, v88, v4
	v_exp_f32_e32 v86, v86
	v_sub_f32_e32 v93, v93, v4
	v_exp_f32_e32 v93, v93
	v_sub_f32_e32 v94, v94, v4
	v_add_f32_e32 v88, v86, v87
	v_add_f32_e32 v6, v88, v6
	v_sub_f32_e32 v88, v89, v4
	v_sub_f32_e32 v89, v105, v4
	v_exp_f32_e32 v88, v88
	v_exp_f32_e32 v89, v89
	v_exp_f32_e32 v94, v94
	v_sub_f32_e32 v95, v95, v4
	v_exp_f32_e32 v95, v95
	v_add_f32_e32 v96, v88, v89
	v_add_f32_e32 v6, v96, v6
	v_sub_f32_e32 v96, v106, v4
	v_exp_f32_e32 v96, v96
	v_add_u32_e32 v14, s18, v218
	s_lshl_b64 s[2:3], s[2:3], 11
	s_add_u32 s2, s31, s2
	v_add_f32_e32 v97, v90, v96
	v_add_f32_e32 v6, v97, v6
	v_sub_f32_e32 v97, v107, v4
	v_exp_f32_e32 v97, v97
	s_addc_u32 s3, s34, s3
	v_add_f32_e32 v98, v91, v97
	v_add_f32_e32 v6, v98, v6
	v_sub_f32_e32 v98, v108, v4
	v_exp_f32_e32 v98, v98
	s_nop 0
	v_add_f32_e32 v99, v92, v98
	v_add_f32_e32 v6, v99, v6
	v_sub_f32_e32 v99, v109, v4
	v_exp_f32_e32 v99, v99
	s_nop 0
	v_add_f32_e32 v100, v93, v99
	v_add_f32_e32 v6, v100, v6
	v_sub_f32_e32 v100, v110, v4
	v_exp_f32_e32 v100, v100
	v_sub_f32_e32 v4, v111, v4
	v_add_f32_e32 v101, v94, v100
	v_add_f32_e32 v6, v101, v6
	v_exp_f32_e32 v101, v4
	s_nop 0
	v_add_f32_e32 v4, v95, v101
	v_add_f32_e32 v102, v4, v6
	v_fmac_f32_e32 v102, v3, v0
	v_add_u32_e32 v0, s19, v217
	v_cvt_pk_bf16_f32 v6, v2, v7
	v_cvt_pk_bf16_f32 v7, v8, v9
	v_cvt_pk_bf16_f32 v8, v13, v80
	v_cvt_pk_bf16_f32 v9, v82, v84
	v_cvt_pk_bf16_f32 v10, v5, v10
	v_cvt_pk_bf16_f32 v11, v11, v12
	v_cvt_pk_bf16_f32 v12, v15, v81
	v_cvt_pk_bf16_f32 v13, v83, v85
	v_cvt_pk_bf16_f32 v80, v86, v88
	v_cvt_pk_bf16_f32 v81, v90, v91
	v_cvt_pk_bf16_f32 v82, v92, v93
	v_cvt_pk_bf16_f32 v83, v94, v95
	v_cvt_pk_bf16_f32 v2, v87, v89
	v_cvt_pk_bf16_f32 v3, v96, v97
	v_cvt_pk_bf16_f32 v4, v98, v99
	v_cvt_pk_bf16_f32 v5, v100, v101
	ds_read_b128 v[84:87], v0 offset:24576
	s_waitcnt lgkmcnt(0)
	v_mfma_f32_32x32x16_bf16 v[64:79], v[84:87], v[6:9], v[64:79]
	ds_read_b128 v[84:87], v0 offset:28672
	s_waitcnt lgkmcnt(0)
	v_mfma_f32_32x32x16_bf16 v[48:63], v[84:87], v[6:9], v[48:63]
	ds_read_b128 v[84:87], v0 offset:32768
	s_waitcnt lgkmcnt(0)
	v_mfma_f32_32x32x16_bf16 v[32:47], v[84:87], v[6:9], v[32:47]
	ds_read_b128 v[84:87], v0 offset:36864
	v_xad_u32 v0, v14, 32, 0
	s_waitcnt lgkmcnt(0)
	v_mfma_f32_32x32x16_bf16 v[16:31], v[84:87], v[6:9], v[16:31]
	ds_read_b128 v[6:9], v0
	s_waitcnt lgkmcnt(0)
	v_mfma_f32_32x32x16_bf16 v[64:79], v[6:9], v[80:83], v[64:79]
	ds_read_b128 v[6:9], v0 offset:4096
	s_waitcnt lgkmcnt(0)
	v_mfma_f32_32x32x16_bf16 v[48:63], v[6:9], v[80:83], v[48:63]
	ds_read_b128 v[6:9], v0 offset:8192
	s_waitcnt lgkmcnt(0)
	v_mfma_f32_32x32x16_bf16 v[32:47], v[6:9], v[80:83], v[32:47]
	ds_read_b128 v[6:9], v0 offset:12288
	v_xad_u32 v0, v14, 64, 0
	s_waitcnt lgkmcnt(0)
	v_mfma_f32_32x32x16_bf16 v[16:31], v[6:9], v[80:83], v[16:31]
	ds_read_b128 v[6:9], v0
	s_waitcnt lgkmcnt(0)
	v_mfma_f32_32x32x16_bf16 v[64:79], v[6:9], v[10:13], v[64:79]
	ds_read_b128 v[6:9], v0 offset:4096
	s_waitcnt lgkmcnt(0)
	v_mfma_f32_32x32x16_bf16 v[48:63], v[6:9], v[10:13], v[48:63]
	ds_read_b128 v[6:9], v0 offset:8192
	s_waitcnt lgkmcnt(0)
	v_mfma_f32_32x32x16_bf16 v[32:47], v[6:9], v[10:13], v[32:47]
	ds_read_b128 v[6:9], v0 offset:12288
	v_xor_b32_e32 v0, 0x60, v14
	v_add_u32_e32 v0, 0, v0
	s_waitcnt lgkmcnt(0)
	v_mfma_f32_32x32x16_bf16 v[16:31], v[6:9], v[10:13], v[16:31]
	ds_read_b128 v[6:9], v0
	s_waitcnt lgkmcnt(0)
	v_mfma_f32_32x32x16_bf16 v[64:79], v[6:9], v[2:5], v[64:79]
	ds_read_b128 v[6:9], v0 offset:4096
	s_waitcnt lgkmcnt(0)
	v_mfma_f32_32x32x16_bf16 v[48:63], v[6:9], v[2:5], v[48:63]
	ds_read_b128 v[6:9], v0 offset:8192
	s_waitcnt lgkmcnt(0)
	v_mfma_f32_32x32x16_bf16 v[32:47], v[6:9], v[2:5], v[32:47]
	ds_read_b128 v[6:9], v0 offset:12288
	ds_bpermute_b32 v0, v219, v102
	s_waitcnt lgkmcnt(0)
	v_add_f32_e32 v0, v102, v0
	v_mfma_f32_32x32x16_bf16 v[16:31], v[6:9], v[2:5], v[16:31]
	v_div_scale_f32 v2, s[18:19], v0, v0, 1.0
	v_rcp_f32_e32 v3, v2
	s_lshl_b32 s18, s42, 1
	s_add_u32 s2, s2, s18
	s_addc_u32 s3, s3, 0
	v_fma_f32 v4, -v2, v3, 1.0
	v_fmac_f32_e32 v3, v4, v3
	v_div_scale_f32 v4, vcc, 1.0, v0, 1.0
	v_mul_f32_e32 v5, v4, v3
	v_fma_f32 v6, -v2, v5, v4
	v_fmac_f32_e32 v5, v6, v3
	v_fma_f32 v2, -v2, v5, v4
	v_div_fmas_f32 v2, v2, v3, v5
	v_div_fixup_f32 v0, v2, v0, 1.0
	v_and_b32_e32 v10, 32, v179
	v_lshrrev_b32_e32 v10, 2, v10
	v_add_u32_e32 v10, v172, v10
	v_mov_b32_e32 v11, v1
	v_lshl_add_u64 v[2:3], s[2:3], 0, v[10:11]
	v_mul_f32_e32 v8, v64, v0
	v_mul_f32_e32 v9, v65, v0
	v_cvt_pk_bf16_f32 v4, v8, v9
	v_mul_f32_e32 v8, v66, v0
	v_mul_f32_e32 v9, v67, v0
	v_cvt_pk_bf16_f32 v5, v8, v9
	v_mul_f32_e32 v8, v68, v0
	v_mul_f32_e32 v9, v69, v0
	v_cvt_pk_bf16_f32 v6, v8, v9
	v_mul_f32_e32 v8, v70, v0
	v_mul_f32_e32 v9, v71, v0
	v_cvt_pk_bf16_f32 v7, v8, v9
	s_nop 1
	v_permlane32_swap_b32_e32 v4, v6
	v_permlane32_swap_b32_e32 v5, v7
	global_store_dwordx4 v[2:3], v[4:7], off
	v_mul_f32_e32 v8, v72, v0
	v_mul_f32_e32 v9, v73, v0
	v_cvt_pk_bf16_f32 v4, v8, v9
	v_mul_f32_e32 v8, v74, v0
	v_mul_f32_e32 v9, v75, v0
	v_cvt_pk_bf16_f32 v5, v8, v9
	v_mul_f32_e32 v8, v76, v0
	v_mul_f32_e32 v9, v77, v0
	v_cvt_pk_bf16_f32 v6, v8, v9
	v_mul_f32_e32 v8, v78, v0
	v_mul_f32_e32 v9, v79, v0
	v_cvt_pk_bf16_f32 v7, v8, v9
	s_nop 1
	v_permlane32_swap_b32_e32 v4, v6
	v_permlane32_swap_b32_e32 v5, v7
	global_store_dwordx4 v[2:3], v[4:7], off offset:32
	v_mul_f32_e32 v8, v48, v0
	v_mul_f32_e32 v9, v49, v0
	v_cvt_pk_bf16_f32 v4, v8, v9
	v_mul_f32_e32 v8, v50, v0
	v_mul_f32_e32 v9, v51, v0
	v_cvt_pk_bf16_f32 v5, v8, v9
	v_mul_f32_e32 v8, v52, v0
	v_mul_f32_e32 v9, v53, v0
	v_cvt_pk_bf16_f32 v6, v8, v9
	v_mul_f32_e32 v8, v54, v0
	v_mul_f32_e32 v9, v55, v0
	v_cvt_pk_bf16_f32 v7, v8, v9
	s_nop 1
	v_permlane32_swap_b32_e32 v4, v6
	v_permlane32_swap_b32_e32 v5, v7
	global_store_dwordx4 v[2:3], v[4:7], off offset:64
	v_mul_f32_e32 v8, v56, v0
	v_mul_f32_e32 v9, v57, v0
	v_cvt_pk_bf16_f32 v4, v8, v9
	v_mul_f32_e32 v8, v58, v0
	v_mul_f32_e32 v9, v59, v0
	v_cvt_pk_bf16_f32 v5, v8, v9
	v_mul_f32_e32 v8, v60, v0
	v_mul_f32_e32 v9, v61, v0
	v_cvt_pk_bf16_f32 v6, v8, v9
	v_mul_f32_e32 v8, v62, v0
	v_mul_f32_e32 v9, v63, v0
	v_cvt_pk_bf16_f32 v7, v8, v9
	s_nop 1
	v_permlane32_swap_b32_e32 v4, v6
	v_permlane32_swap_b32_e32 v5, v7
	global_store_dwordx4 v[2:3], v[4:7], off offset:96
	v_mul_f32_e32 v8, v32, v0
	v_mul_f32_e32 v9, v33, v0
	v_cvt_pk_bf16_f32 v4, v8, v9
	v_mul_f32_e32 v8, v34, v0
	v_mul_f32_e32 v9, v35, v0
	v_cvt_pk_bf16_f32 v5, v8, v9
	v_mul_f32_e32 v8, v36, v0
	v_mul_f32_e32 v9, v37, v0
	v_cvt_pk_bf16_f32 v6, v8, v9
	v_mul_f32_e32 v8, v38, v0
	v_mul_f32_e32 v9, v39, v0
	v_cvt_pk_bf16_f32 v7, v8, v9
	s_nop 1
	v_permlane32_swap_b32_e32 v4, v6
	v_permlane32_swap_b32_e32 v5, v7
	global_store_dwordx4 v[2:3], v[4:7], off offset:128
	v_mul_f32_e32 v8, v40, v0
	v_mul_f32_e32 v9, v41, v0
	v_cvt_pk_bf16_f32 v4, v8, v9
	v_mul_f32_e32 v8, v42, v0
	v_mul_f32_e32 v9, v43, v0
	v_cvt_pk_bf16_f32 v5, v8, v9
	v_mul_f32_e32 v8, v44, v0
	v_mul_f32_e32 v9, v45, v0
	v_cvt_pk_bf16_f32 v6, v8, v9
	v_mul_f32_e32 v8, v46, v0
	v_mul_f32_e32 v9, v47, v0
	v_cvt_pk_bf16_f32 v7, v8, v9
	s_nop 1
	v_permlane32_swap_b32_e32 v4, v6
	v_permlane32_swap_b32_e32 v5, v7
	global_store_dwordx4 v[2:3], v[4:7], off offset:160
	v_mul_f32_e32 v8, v16, v0
	v_mul_f32_e32 v9, v17, v0
	v_cvt_pk_bf16_f32 v4, v8, v9
	v_mul_f32_e32 v8, v18, v0
	v_mul_f32_e32 v9, v19, v0
	v_cvt_pk_bf16_f32 v5, v8, v9
	v_mul_f32_e32 v8, v20, v0
	v_mul_f32_e32 v9, v21, v0
	v_cvt_pk_bf16_f32 v6, v8, v9
	v_mul_f32_e32 v8, v22, v0
	v_mul_f32_e32 v9, v23, v0
	v_cvt_pk_bf16_f32 v7, v8, v9
	s_nop 1
	v_permlane32_swap_b32_e32 v4, v6
	v_permlane32_swap_b32_e32 v5, v7
	global_store_dwordx4 v[2:3], v[4:7], off offset:192
	v_mul_f32_e32 v8, v24, v0
	v_mul_f32_e32 v9, v25, v0
	v_cvt_pk_bf16_f32 v4, v8, v9
	v_mul_f32_e32 v8, v26, v0
	v_mul_f32_e32 v9, v27, v0
	v_cvt_pk_bf16_f32 v5, v8, v9
	v_mul_f32_e32 v8, v28, v0
	v_mul_f32_e32 v9, v29, v0
	v_cvt_pk_bf16_f32 v6, v8, v9
	v_mul_f32_e32 v8, v30, v0
	v_mul_f32_e32 v9, v31, v0
	v_cvt_pk_bf16_f32 v7, v8, v9
	s_nop 1
	v_permlane32_swap_b32_e32 v4, v6
	v_permlane32_swap_b32_e32 v5, v7
	global_store_dwordx4 v[2:3], v[4:7], off offset:224
	s_add_i32 s16, s16, s64
	s_cmpk_gt_i32 s16, 0x27f
	s_cbranch_scc1 .LBB0_605

.LBB0_596:
	s_and_b32 s54, s2, 7
	s_add_i32 s2, s3, s37
	s_ashr_i32 s3, s2, 31
	s_mul_i32 s42, s2, 0xc00
	s_mul_hi_i32 s19, s2, 0xc00
	s_add_u32 s42, s22, s42
	s_addc_u32 s19, s23, s19
	s_mul_i32 s44, s54, 0x180
	s_add_u32 s44, s42, s44
	s_addc_u32 s45, s19, 0
	s_ashr_i32 s19, s18, 31
	v_lshl_add_u64 v[2:3], s[44:45], 0, v[170:171]
	s_lshl_b64 s[44:45], s[18:19], 11
	s_add_u32 s46, s25, s44
	s_addc_u32 s47, s26, s45
	s_lshl_b32 s42, s54, 7
	s_lshl_b32 s56, s54, 8
	s_add_u32 s46, s46, s56
	s_addc_u32 s47, s47, 0
	s_lshl_b64 s[48:49], s[18:19], 7
	s_add_u32 s50, s17, s48
	s_addc_u32 s51, s21, s49
	s_mul_i32 s57, s54, 0x580000
	s_add_u32 s60, s27, s57
	s_addc_u32 s61, s30, 0
	s_lshl_b64 s[54:55], s[18:19], 1
	s_add_u32 s18, s60, s54
	s_addc_u32 s19, s61, s55
	s_add_i32 s60, s39, 0
	global_load_dwordx4 v[156:159], v[2:3], off
	global_load_dwordx4 v[152:155], v[2:3], off offset:32
	global_load_dwordx4 v[148:151], v[2:3], off offset:64
	global_load_dwordx4 v[144:147], v[2:3], off offset:96
	global_load_dwordx4 v[140:143], v[2:3], off offset:128
	global_load_dwordx4 v[136:139], v[2:3], off offset:160
	global_load_dwordx4 v[132:135], v[2:3], off offset:192
	global_load_dwordx4 v[128:131], v[2:3], off offset:224
	global_load_dwordx4 v[124:127], v[2:3], off offset:256
	global_load_dwordx4 v[120:123], v[2:3], off offset:288
	global_load_dwordx4 v[116:119], v[2:3], off offset:320
	global_load_dwordx4 v[112:115], v[2:3], off offset:352
	s_waitcnt lgkmcnt(0)
	s_barrier
	v_lshl_add_u64 v[2:3], s[46:47], 0, v[166:167]
	s_mov_b32 m0, s60
	v_lshl_add_u64 v[4:5], s[18:19], 0, v[160:161]
	global_load_lds_dwordx4 v[2:3], off
	v_lshl_add_u64 v[2:3], s[46:47], 0, v[168:169]
	s_add_i32 m0, s60, 0x400
	v_lshl_add_u64 v[6:7], s[18:19], 0, v[162:163]
	global_load_lds_dwordx4 v[2:3], off
	v_lshl_add_u64 v[2:3], s[50:51], 0, v[164:165]
	s_add_i32 s50, s41, 0
	s_add_i32 m0, s50, 0x4000
	v_mov_b32_e32 v14, v1
	global_load_lds_dwordx4 v[2:3], off
	s_add_i32 m0, s60, 0x6000
	v_lshl_add_u64 v[2:3], v[2:3], 0, s[28:29]
	global_load_lds_dwordx4 v[4:5], off
	s_add_i32 m0, s60, 0x6400
	s_add_u32 s18, s46, 0x20000
	s_addc_u32 s19, s47, 0
	global_load_lds_dwordx4 v[6:7], off
	v_lshl_add_u64 v[8:9], s[18:19], 0, v[166:167]
	s_add_i32 m0, s60, 0xa000
	v_mov_b32_e32 v15, v1
	global_load_lds_dwordx4 v[8:9], off
	v_lshl_add_u64 v[8:9], s[18:19], 0, v[168:169]
	s_add_i32 m0, s60, 0xa400
	s_add_i32 s18, 0, 0x10000
	global_load_lds_dwordx4 v[8:9], off
	s_add_i32 m0, s50, 0xe000
	v_mov_b32_e32 v0, v1
	global_load_lds_dwordx4 v[2:3], off
	v_lshl_add_u64 v[2:3], v[4:5], 0, s[76:77]
	s_add_i32 m0, s18, s39
	v_mov_b32_e32 v4, v1
	global_load_lds_dwordx4 v[2:3], off
	v_lshl_add_u64 v[2:3], v[6:7], 0, s[76:77]
	s_add_i32 m0, s18, s40
	s_add_u32 s46, s54, s57
	global_load_lds_dwordx4 v[2:3], off
	s_addc_u32 s47, s55, 0
	s_or_b32 s44, s44, s56
	v_mov_b32_e32 v2, v1
	v_mov_b32_e32 v3, v1
	v_mov_b32_e32 v5, v1
	v_mov_b32_e32 v6, v1
	v_mov_b32_e32 v7, v1
	v_mov_b32_e32 v8, v1
	v_mov_b32_e32 v9, v1
	v_mov_b32_e32 v10, v1
	v_mov_b32_e32 v11, v1
	v_mov_b32_e32 v12, v1
	v_mov_b32_e32 v13, v1
	v_mov_b64_e32 v[30:31], v[14:15]
	v_mov_b64_e32 v[46:47], v[14:15]
	v_mov_b64_e32 v[62:63], v[14:15]
	v_mov_b64_e32 v[78:79], v[14:15]
	v_readlane_b32 s54, v255, 36
	s_mov_b32 s19, 1
	v_lshl_add_u64 v[204:205], s[46:47], 0, v[194:195]
	v_lshl_add_u64 v[206:207], s[46:47], 0, v[196:197]
	v_lshl_add_u64 v[208:209], v[198:199], 0, s[48:49]
	v_lshl_add_u64 v[210:211], s[44:45], 0, v[200:201]
	v_lshl_add_u64 v[212:213], s[44:45], 0, v[202:203]
	s_mov_b32 s18, 0
	v_mov_b32_e32 v220, 0
	v_mov_b32_e32 v221, 0xf149f2ca
	v_mov_b64_e32 v[28:29], v[12:13]
	v_mov_b64_e32 v[26:27], v[10:11]
	v_mov_b64_e32 v[24:25], v[8:9]
	v_mov_b64_e32 v[22:23], v[6:7]
	v_mov_b64_e32 v[20:21], v[4:5]
	v_mov_b64_e32 v[18:19], v[2:3]
	v_mov_b64_e32 v[16:17], v[0:1]
	v_mov_b64_e32 v[44:45], v[12:13]
	v_mov_b64_e32 v[42:43], v[10:11]
	v_mov_b64_e32 v[40:41], v[8:9]
	v_mov_b64_e32 v[38:39], v[6:7]
	v_mov_b64_e32 v[36:37], v[4:5]
	v_mov_b64_e32 v[34:35], v[2:3]
	v_mov_b64_e32 v[32:33], v[0:1]
	v_mov_b64_e32 v[60:61], v[12:13]
	v_mov_b64_e32 v[58:59], v[10:11]
	v_mov_b64_e32 v[56:57], v[8:9]
	v_mov_b64_e32 v[54:55], v[6:7]
	v_mov_b64_e32 v[52:53], v[4:5]
	v_mov_b64_e32 v[50:51], v[2:3]
	v_mov_b64_e32 v[48:49], v[0:1]
	v_mov_b64_e32 v[76:77], v[12:13]
	v_mov_b64_e32 v[74:75], v[10:11]
	v_mov_b64_e32 v[72:73], v[8:9]
	v_mov_b64_e32 v[70:71], v[6:7]
	v_mov_b64_e32 v[68:69], v[4:5]
	v_mov_b64_e32 v[66:67], v[2:3]
	v_mov_b64_e32 v[64:65], v[0:1]
	v_readlane_b32 s55, v255, 37
	v_readlane_b32 s56, v254, 6
	s_mov_b32 s60, 0x1c000
	v_readlane_b32 s57, v254, 7
	s_waitcnt vmcnt(5)

.Lattn_nodma_A:
	v_lshl_add_u64 v[204:205], v[204:205], 0, s[76:77]
	v_lshl_add_u64 v[206:207], v[206:207], 0, s[76:77]
	v_lshl_add_u64 v[208:209], v[208:209], 0, s[28:29]
	v_lshl_add_u64 v[210:211], v[210:211], 0, s[52:53]
	v_lshl_add_u64 v[212:213], v[212:213], 0, s[52:53]
	s_waitcnt lgkmcnt(4)
	v_mfma_f32_32x32x16_bf16 v[80:95], v[2:5], v[156:159], 0
	v_mfma_f32_32x32x16_bf16 v[96:111], v[6:9], v[156:159], 0
	v_xor_b32_e32 v10, 0x60, v0
	ds_read_b128 v[2:5], v10
	ds_read_b128 v[6:9], v10 offset:8192
	s_waitcnt lgkmcnt(4)
	v_mfma_f32_32x32x16_bf16 v[80:95], v[244:247], v[152:155], v[80:95]
	v_mfma_f32_32x32x16_bf16 v[96:111], v[248:251], v[152:155], v[96:111]
	v_xor_b32_e32 v10, 0x80, v0
	ds_read_b128 v[244:247], v10
	ds_read_b128 v[248:251], v10 offset:8192
	s_waitcnt lgkmcnt(4)
	v_mfma_f32_32x32x16_bf16 v[80:95], v[12:15], v[148:151], v[80:95]
	v_mfma_f32_32x32x16_bf16 v[96:111], v[224:227], v[148:151], v[96:111]
	v_xor_b32_e32 v10, 0xa0, v0
	ds_read_b128 v[12:15], v10
	ds_read_b128 v[224:227], v10 offset:8192
	s_waitcnt lgkmcnt(4)
	v_mfma_f32_32x32x16_bf16 v[80:95], v[2:5], v[144:147], v[80:95]
	v_mfma_f32_32x32x16_bf16 v[96:111], v[6:9], v[144:147], v[96:111]
	v_xor_b32_e32 v10, 0xc0, v0
	ds_read_b128 v[2:5], v10
	ds_read_b128 v[6:9], v10 offset:8192
	s_waitcnt lgkmcnt(4)
	v_mfma_f32_32x32x16_bf16 v[80:95], v[244:247], v[140:143], v[80:95]
	v_mfma_f32_32x32x16_bf16 v[96:111], v[248:251], v[140:143], v[96:111]
	v_xor_b32_e32 v10, 0xe0, v0
	ds_read_b128 v[244:247], v10
	ds_read_b128 v[248:251], v10 offset:8192
	s_waitcnt lgkmcnt(4)
	v_mfma_f32_32x32x16_bf16 v[80:95], v[12:15], v[136:139], v[80:95]
	v_mfma_f32_32x32x16_bf16 v[96:111], v[224:227], v[136:139], v[96:111]
	v_add_u32_e32 v10, s18, v215
	ds_read_b128 v[12:15], v10 offset:16384
	ds_read_b128 v[224:227], v10 offset:20480
	s_waitcnt lgkmcnt(4)
	v_mfma_f32_32x32x16_bf16 v[80:95], v[2:5], v[132:135], v[80:95]
	v_mfma_f32_32x32x16_bf16 v[96:111], v[6:9], v[132:135], v[96:111]
	v_add_u32_e32 v11, s18, v216
	v_xad_u32 v10, v11, 32, 0
	ds_read_b128 v[2:5], v10
	ds_read_b128 v[6:9], v10 offset:4096
	s_waitcnt lgkmcnt(4)
	v_mfma_f32_32x32x16_bf16 v[80:95], v[244:247], v[128:131], v[80:95]
	v_mfma_f32_32x32x16_bf16 v[96:111], v[248:251], v[128:131], v[96:111]
	v_xad_u32 v10, v11, 64, 0
	ds_read_b128 v[244:247], v10
	ds_read_b128 v[248:251], v10 offset:4096
	s_waitcnt lgkmcnt(4)
	v_mfma_f32_32x32x16_bf16 v[80:95], v[12:15], v[124:127], v[80:95]
	v_mfma_f32_32x32x16_bf16 v[96:111], v[224:227], v[124:127], v[96:111]
	v_xor_b32_e32 v10, 0x60, v11
	ds_read_b128 v[12:15], v10
	ds_read_b128 v[224:227], v10 offset:4096
	s_waitcnt lgkmcnt(4)
	v_mfma_f32_32x32x16_bf16 v[80:95], v[2:5], v[120:123], v[80:95]
	v_mfma_f32_32x32x16_bf16 v[96:111], v[6:9], v[120:123], v[96:111]
	v_add_u32_e32 v228, s18, v217
	s_waitcnt lgkmcnt(2)
	v_mfma_f32_32x32x16_bf16 v[80:95], v[244:247], v[116:119], v[80:95]
	v_mfma_f32_32x32x16_bf16 v[96:111], v[248:251], v[116:119], v[96:111]
	ds_read_b128 v[244:247], v228 offset:24576
	ds_read_b128 v[248:251], v228 offset:28672
	s_waitcnt lgkmcnt(2)
	v_mfma_f32_32x32x16_bf16 v[80:95], v[12:15], v[112:115], v[80:95]
	v_mfma_f32_32x32x16_bf16 v[96:111], v[224:227], v[112:115], v[96:111]
	v_add_u32_e32 v229, s18, v218
	v_xad_u32 v243, v229, 32, 0
	v_xad_u32 v252, v229, 64, 0
	v_xor_b32_e32 v253, 0x60, v229
	s_nop 7
	s_nop 0
	v_max_f32_e32 v0, v81, v81
	v_max_f32_e32 v2, v80, v80
	v_max_f32_e32 v0, v2, v0
	v_max3_f32 v0, v0, v82, v83
	v_max3_f32 v0, v0, v84, v85
	v_max3_f32 v0, v0, v86, v87
	v_max3_f32 v0, v0, v88, v89
	v_max3_f32 v0, v0, v90, v91
	v_max3_f32 v0, v0, v92, v93
	v_max3_f32 v0, v0, v94, v95
	v_max3_f32 v0, v0, v96, v97
	v_max3_f32 v0, v0, v98, v99
	v_max3_f32 v0, v0, v100, v101
	v_max3_f32 v0, v0, v102, v103
	v_max3_f32 v0, v0, v104, v105
	v_max3_f32 v0, v0, v106, v107
	v_max3_f32 v0, v0, v108, v109
	v_max3_f32 v0, v0, v110, v111
	ds_bpermute_b32 v2, v219, v0
	s_waitcnt lgkmcnt(0)
	v_max3_f32 v2, v221, v0, v2
	v_sub_f32_e32 v0, v221, v2
	v_exp_f32_e32 v0, v0
	v_cmp_gt_f32_e32 vcc, v2, v221
	s_cbranch_vccz .Lattn_noscale_A
	v_pk_mul_f32 v[78:79], v[78:79], v[0:1] op_sel_hi:[1,0]
	v_pk_mul_f32 v[76:77], v[76:77], v[0:1] op_sel_hi:[1,0]
	v_pk_mul_f32 v[74:75], v[74:75], v[0:1] op_sel_hi:[1,0]
	v_pk_mul_f32 v[72:73], v[72:73], v[0:1] op_sel_hi:[1,0]
	v_pk_mul_f32 v[70:71], v[70:71], v[0:1] op_sel_hi:[1,0]
	v_pk_mul_f32 v[68:69], v[68:69], v[0:1] op_sel_hi:[1,0]
	v_pk_mul_f32 v[66:67], v[66:67], v[0:1] op_sel_hi:[1,0]
	v_pk_mul_f32 v[64:65], v[64:65], v[0:1] op_sel_hi:[1,0]
	v_pk_mul_f32 v[62:63], v[62:63], v[0:1] op_sel_hi:[1,0]
	v_pk_mul_f32 v[60:61], v[60:61], v[0:1] op_sel_hi:[1,0]
	v_pk_mul_f32 v[58:59], v[58:59], v[0:1] op_sel_hi:[1,0]
	v_pk_mul_f32 v[56:57], v[56:57], v[0:1] op_sel_hi:[1,0]
	v_pk_mul_f32 v[54:55], v[54:55], v[0:1] op_sel_hi:[1,0]
	v_pk_mul_f32 v[52:53], v[52:53], v[0:1] op_sel_hi:[1,0]
	v_pk_mul_f32 v[50:51], v[50:51], v[0:1] op_sel_hi:[1,0]
	v_pk_mul_f32 v[48:49], v[48:49], v[0:1] op_sel_hi:[1,0]
	v_pk_mul_f32 v[46:47], v[46:47], v[0:1] op_sel_hi:[1,0]
	v_pk_mul_f32 v[44:45], v[44:45], v[0:1] op_sel_hi:[1,0]
	v_pk_mul_f32 v[42:43], v[42:43], v[0:1] op_sel_hi:[1,0]
	v_pk_mul_f32 v[40:41], v[40:41], v[0:1] op_sel_hi:[1,0]
	v_pk_mul_f32 v[38:39], v[38:39], v[0:1] op_sel_hi:[1,0]
	v_pk_mul_f32 v[36:37], v[36:37], v[0:1] op_sel_hi:[1,0]
	v_pk_mul_f32 v[34:35], v[34:35], v[0:1] op_sel_hi:[1,0]
	v_pk_mul_f32 v[32:33], v[32:33], v[0:1] op_sel_hi:[1,0]
	v_pk_mul_f32 v[30:31], v[30:31], v[0:1] op_sel_hi:[1,0]
	v_pk_mul_f32 v[28:29], v[28:29], v[0:1] op_sel_hi:[1,0]
	v_pk_mul_f32 v[26:27], v[26:27], v[0:1] op_sel_hi:[1,0]
	v_pk_mul_f32 v[24:25], v[24:25], v[0:1] op_sel_hi:[1,0]
	v_pk_mul_f32 v[22:23], v[22:23], v[0:1] op_sel_hi:[1,0]
	v_pk_mul_f32 v[20:21], v[20:21], v[0:1] op_sel_hi:[1,0]
	v_pk_mul_f32 v[18:19], v[18:19], v[0:1] op_sel_hi:[1,0]
	v_pk_mul_f32 v[16:17], v[16:17], v[0:1] op_sel_hi:[1,0]
.Lattn_noscale_A:
	v_pk_add_f32 v[80:81], v[80:81], v[2:3] op_sel_hi:[1,0] neg_lo:[0,1] neg_hi:[0,1]
	v_pk_add_f32 v[96:97], v[96:97], v[2:3] op_sel_hi:[1,0] neg_lo:[0,1] neg_hi:[0,1]
	v_exp_f32_e32 v80, v80
	v_exp_f32_e32 v81, v81
	v_exp_f32_e32 v96, v96
	v_exp_f32_e32 v97, v97
	v_pk_add_f32 v[82:83], v[82:83], v[2:3] op_sel_hi:[1,0] neg_lo:[0,1] neg_hi:[0,1]
	v_pk_add_f32 v[98:99], v[98:99], v[2:3] op_sel_hi:[1,0] neg_lo:[0,1] neg_hi:[0,1]
	v_exp_f32_e32 v82, v82
	v_exp_f32_e32 v83, v83
	v_exp_f32_e32 v98, v98
	v_exp_f32_e32 v99, v99
	v_pk_add_f32 v[84:85], v[84:85], v[2:3] op_sel_hi:[1,0] neg_lo:[0,1] neg_hi:[0,1]
	v_pk_add_f32 v[100:101], v[100:101], v[2:3] op_sel_hi:[1,0] neg_lo:[0,1] neg_hi:[0,1]
	v_exp_f32_e32 v84, v84
	v_exp_f32_e32 v85, v85
	v_exp_f32_e32 v100, v100
	v_exp_f32_e32 v101, v101
	v_pk_add_f32 v[86:87], v[86:87], v[2:3] op_sel_hi:[1,0] neg_lo:[0,1] neg_hi:[0,1]
	v_pk_add_f32 v[102:103], v[102:103], v[2:3] op_sel_hi:[1,0] neg_lo:[0,1] neg_hi:[0,1]
	v_exp_f32_e32 v86, v86
	v_exp_f32_e32 v87, v87
	v_exp_f32_e32 v102, v102
	v_exp_f32_e32 v103, v103
	v_cvt_pk_bf16_f32 v4, v80, v81
	v_cvt_pk_bf16_f32 v5, v82, v83
	v_cvt_pk_bf16_f32 v6, v84, v85
	v_cvt_pk_bf16_f32 v7, v86, v87
	v_cvt_pk_bf16_f32 v8, v96, v97
	v_cvt_pk_bf16_f32 v9, v98, v99
	v_cvt_pk_bf16_f32 v10, v100, v101
	v_cvt_pk_bf16_f32 v11, v102, v103
	v_pk_add_f32 v[80:81], v[80:81], v[96:97]
	v_pk_add_f32 v[82:83], v[82:83], v[98:99]
	v_pk_add_f32 v[84:85], v[84:85], v[100:101]
	v_pk_add_f32 v[86:87], v[86:87], v[102:103]
	ds_read_b128 v[96:99], v228 offset:32768
	ds_read_b128 v[100:103], v228 offset:36864
	v_mfma_f32_32x32x16_bf16 v[64:79], v[244:247], v[4:7], v[64:79]
	ds_read_b128 v[244:247], v243
	v_pk_add_f32 v[88:89], v[88:89], v[2:3] op_sel_hi:[1,0] neg_lo:[0,1] neg_hi:[0,1]
	v_pk_add_f32 v[104:105], v[104:105], v[2:3] op_sel_hi:[1,0] neg_lo:[0,1] neg_hi:[0,1]
	v_exp_f32_e32 v88, v88
	v_exp_f32_e32 v89, v89
	v_exp_f32_e32 v104, v104
	v_exp_f32_e32 v105, v105
	v_mfma_f32_32x32x16_bf16 v[48:63], v[248:251], v[4:7], v[48:63]
	ds_read_b128 v[248:251], v243 offset:4096
	v_pk_add_f32 v[90:91], v[90:91], v[2:3] op_sel_hi:[1,0] neg_lo:[0,1] neg_hi:[0,1]
	v_pk_add_f32 v[106:107], v[106:107], v[2:3] op_sel_hi:[1,0] neg_lo:[0,1] neg_hi:[0,1]
	v_exp_f32_e32 v90, v90
	v_exp_f32_e32 v91, v91
	v_exp_f32_e32 v106, v106
	v_exp_f32_e32 v107, v107
	s_waitcnt lgkmcnt(3)
	v_mfma_f32_32x32x16_bf16 v[32:47], v[96:99], v[4:7], v[32:47]
	ds_read_b128 v[96:99], v243 offset:8192
	v_pk_add_f32 v[92:93], v[92:93], v[2:3] op_sel_hi:[1,0] neg_lo:[0,1] neg_hi:[0,1]
	v_pk_add_f32 v[108:109], v[108:109], v[2:3] op_sel_hi:[1,0] neg_lo:[0,1] neg_hi:[0,1]
	v_exp_f32_e32 v92, v92
	v_exp_f32_e32 v93, v93
	v_exp_f32_e32 v108, v108
	v_exp_f32_e32 v109, v109
	s_waitcnt lgkmcnt(3)
	v_mfma_f32_32x32x16_bf16 v[16:31], v[100:103], v[4:7], v[16:31]
	ds_read_b128 v[100:103], v243 offset:12288
	v_pk_add_f32 v[94:95], v[94:95], v[2:3] op_sel_hi:[1,0] neg_lo:[0,1] neg_hi:[0,1]
	v_pk_add_f32 v[110:111], v[110:111], v[2:3] op_sel_hi:[1,0] neg_lo:[0,1] neg_hi:[0,1]
	v_exp_f32_e32 v94, v94
	v_exp_f32_e32 v95, v95
	v_exp_f32_e32 v110, v110
	v_exp_f32_e32 v111, v111
	v_cvt_pk_bf16_f32 v12, v88, v89
	v_cvt_pk_bf16_f32 v13, v90, v91
	v_cvt_pk_bf16_f32 v14, v92, v93
	v_cvt_pk_bf16_f32 v15, v94, v95
	v_cvt_pk_bf16_f32 v224, v104, v105
	v_cvt_pk_bf16_f32 v225, v106, v107
	v_cvt_pk_bf16_f32 v226, v108, v109
	v_cvt_pk_bf16_f32 v227, v110, v111
	v_pk_add_f32 v[88:89], v[88:89], v[104:105]
	v_pk_add_f32 v[90:91], v[90:91], v[106:107]
	v_pk_add_f32 v[92:93], v[92:93], v[108:109]
	v_pk_add_f32 v[94:95], v[94:95], v[110:111]
	v_add_f32_e32 v3, 0, v80
	s_waitcnt lgkmcnt(3)
	v_mfma_f32_32x32x16_bf16 v[64:79], v[244:247], v[12:15], v[64:79]
	ds_read_b128 v[244:247], v252
	v_add_f32_e32 v3, v81, v3
	v_add_f32_e32 v3, v82, v3
	s_waitcnt lgkmcnt(3)
	v_mfma_f32_32x32x16_bf16 v[48:63], v[248:251], v[12:15], v[48:63]
	ds_read_b128 v[248:251], v252 offset:4096
	v_add_f32_e32 v3, v83, v3
	v_add_f32_e32 v3, v84, v3
	s_waitcnt lgkmcnt(3)
	v_mfma_f32_32x32x16_bf16 v[32:47], v[96:99], v[12:15], v[32:47]
	ds_read_b128 v[96:99], v252 offset:8192
	v_add_f32_e32 v3, v85, v3
	v_add_f32_e32 v3, v86, v3
	s_waitcnt lgkmcnt(3)
	v_mfma_f32_32x32x16_bf16 v[16:31], v[100:103], v[12:15], v[16:31]
	ds_read_b128 v[100:103], v252 offset:12288
	v_add_f32_e32 v3, v87, v3
	v_add_f32_e32 v3, v88, v3
	s_waitcnt lgkmcnt(3)
	v_mfma_f32_32x32x16_bf16 v[64:79], v[244:247], v[8:11], v[64:79]
	ds_read_b128 v[244:247], v253
	v_add_f32_e32 v3, v89, v3
	s_waitcnt lgkmcnt(3)
	v_mfma_f32_32x32x16_bf16 v[48:63], v[248:251], v[8:11], v[48:63]
	ds_read_b128 v[248:251], v253 offset:4096
	v_add_f32_e32 v3, v90, v3
	s_waitcnt lgkmcnt(3)
	v_mfma_f32_32x32x16_bf16 v[32:47], v[96:99], v[8:11], v[32:47]
	ds_read_b128 v[96:99], v253 offset:8192
	v_add_f32_e32 v3, v91, v3
	s_waitcnt lgkmcnt(3)
	v_mfma_f32_32x32x16_bf16 v[16:31], v[100:103], v[8:11], v[16:31]
	ds_read_b128 v[100:103], v253 offset:12288
	v_add_f32_e32 v3, v92, v3
	s_waitcnt lgkmcnt(3)
	v_mfma_f32_32x32x16_bf16 v[64:79], v[244:247], v[224:227], v[64:79]
	v_add_f32_e32 v3, v93, v3
	s_waitcnt lgkmcnt(2)
	v_mfma_f32_32x32x16_bf16 v[48:63], v[248:251], v[224:227], v[48:63]
	v_add_f32_e32 v3, v94, v3
	s_waitcnt lgkmcnt(1)
	v_mfma_f32_32x32x16_bf16 v[32:47], v[96:99], v[224:227], v[32:47]
	v_add_f32_e32 v3, v95, v3
	s_waitcnt lgkmcnt(0)
	v_mfma_f32_32x32x16_bf16 v[16:31], v[100:103], v[224:227], v[16:31]
	v_fmac_f32_e32 v3, v220, v0
	s_add_i32 s44, s18, 0xa000
	s_cmp_lg_u32 s18, 0x14000
	s_cselect_b32 s18, s44, 0
	s_cmp_eq_u32 s43, s19
	s_cbranch_scc1 .LBB0_603
	v_mov_b32_e32 v221, v2
	v_mov_b32_e32 v220, v3
	s_branch .LBB0_597

.LBB0_689:
	s_ashr_i32 s57, s56, 31
	s_lshl_b64 s[18:19], s[56:57], 19
	s_add_u32 s60, s17, s18
	s_addc_u32 s61, s21, s19
	s_ashr_i32 s37, s36, 31
	s_lshl_b64 s[18:19], s[36:37], 19
	s_add_u32 s62, s22, s18
	v_mov_b32_e32 v141, 0
	s_addc_u32 s63, s23, s19
	s_andn2_b64 vcc, exec, s[46:47]
	s_waitcnt lgkmcnt(0)
	s_cbranch_vccnz .LBB0_693
	s_and_b64 s[18:19], s[42:43], exec
	s_cselect_b32 s1, s61, s27
	s_cselect_b32 s37, s60, s26
	s_cselect_b32 s57, s63, s3
	s_cselect_b32 s89, s62, s2
	s_add_u32 vcc_lo, s26, 0x100
	s_addc_u32 vcc_hi, s27, 0
	s_add_u32 s90, s2, 0x100
	s_addc_u32 s91, s3, 0
	s_add_u32 s2, s26, 0x40080
	v_mov_b32_e32 v2, 0
	s_addc_u32 s3, s27, 0
	s_mov_b32 s18, 0
	v_mov_b32_e32 v3, v2
	v_mov_b32_e32 v4, v2
	v_mov_b32_e32 v5, v2
	v_mov_b32_e32 v6, v2
	v_mov_b32_e32 v7, v2
	v_mov_b32_e32 v8, v2
	v_mov_b32_e32 v9, v2
	v_mov_b32_e32 v18, v2
	v_mov_b32_e32 v19, v2
	v_mov_b32_e32 v20, v2
	v_mov_b32_e32 v21, v2
	v_mov_b32_e32 v22, v2
	v_mov_b32_e32 v23, v2
	v_mov_b32_e32 v24, v2
	v_mov_b32_e32 v25, v2
	v_mov_b32_e32 v34, v2
	v_mov_b32_e32 v35, v2
	v_mov_b32_e32 v36, v2
	v_mov_b32_e32 v37, v2
	v_mov_b32_e32 v38, v2
	v_mov_b32_e32 v39, v2
	v_mov_b32_e32 v40, v2
	v_mov_b32_e32 v41, v2
	v_mov_b32_e32 v50, v2
	v_mov_b32_e32 v51, v2
	v_mov_b32_e32 v52, v2
	v_mov_b32_e32 v53, v2
	v_mov_b32_e32 v54, v2
	v_mov_b32_e32 v55, v2
	v_mov_b32_e32 v56, v2
	v_mov_b32_e32 v57, v2
	v_mov_b32_e32 v10, v2
	v_mov_b32_e32 v11, v2
	v_mov_b32_e32 v12, v2
	v_mov_b32_e32 v13, v2
	v_mov_b32_e32 v14, v2
	v_mov_b32_e32 v15, v2
	v_mov_b32_e32 v16, v2
	v_mov_b32_e32 v17, v2
	v_mov_b32_e32 v26, v2
	v_mov_b32_e32 v27, v2
	v_mov_b32_e32 v28, v2
	v_mov_b32_e32 v29, v2
	v_mov_b32_e32 v30, v2
	v_mov_b32_e32 v31, v2
	v_mov_b32_e32 v32, v2
	v_mov_b32_e32 v33, v2
	v_mov_b32_e32 v42, v2
	v_mov_b32_e32 v43, v2
	v_mov_b32_e32 v44, v2
	v_mov_b32_e32 v45, v2
	v_mov_b32_e32 v46, v2
	v_mov_b32_e32 v47, v2
	v_mov_b32_e32 v48, v2
	v_mov_b32_e32 v49, v2
	v_mov_b32_e32 v58, v2
	v_mov_b32_e32 v59, v2
	v_mov_b32_e32 v60, v2
	v_mov_b32_e32 v61, v2
	v_mov_b32_e32 v62, v2
	v_mov_b32_e32 v63, v2
	v_mov_b32_e32 v64, v2
	v_mov_b32_e32 v65, v2
	v_mov_b32_e32 v82, v2
	v_mov_b32_e32 v83, v2
	v_mov_b32_e32 v84, v2
	v_mov_b32_e32 v85, v2
	v_mov_b32_e32 v86, v2
	v_mov_b32_e32 v87, v2
	v_mov_b32_e32 v88, v2
	v_mov_b32_e32 v89, v2
	v_mov_b32_e32 v98, v2
	v_mov_b32_e32 v99, v2
	v_mov_b32_e32 v100, v2
	v_mov_b32_e32 v101, v2
	v_mov_b32_e32 v102, v2
	v_mov_b32_e32 v103, v2
	v_mov_b32_e32 v104, v2
	v_mov_b32_e32 v105, v2
	v_mov_b32_e32 v114, v2
	v_mov_b32_e32 v115, v2
	v_mov_b32_e32 v116, v2
	v_mov_b32_e32 v117, v2
	v_mov_b32_e32 v118, v2
	v_mov_b32_e32 v119, v2
	v_mov_b32_e32 v120, v2
	v_mov_b32_e32 v121, v2
	v_mov_b32_e32 v130, v2
	v_mov_b32_e32 v131, v2
	v_mov_b32_e32 v132, v2
	v_mov_b32_e32 v133, v2
	v_mov_b32_e32 v134, v2
	v_mov_b32_e32 v135, v2
	v_mov_b32_e32 v136, v2
	v_mov_b32_e32 v137, v2
	v_mov_b32_e32 v90, v2
	v_mov_b32_e32 v91, v2
	v_mov_b32_e32 v92, v2
	v_mov_b32_e32 v93, v2
	v_mov_b32_e32 v94, v2
	v_mov_b32_e32 v95, v2
	v_mov_b32_e32 v96, v2
	v_mov_b32_e32 v97, v2
	v_mov_b32_e32 v106, v2
	v_mov_b32_e32 v107, v2
	v_mov_b32_e32 v108, v2
	v_mov_b32_e32 v109, v2
	v_mov_b32_e32 v110, v2
	v_mov_b32_e32 v111, v2
	v_mov_b32_e32 v112, v2
	v_mov_b32_e32 v113, v2
	v_mov_b32_e32 v122, v2
	v_mov_b32_e32 v123, v2
	v_mov_b32_e32 v124, v2
	v_mov_b32_e32 v125, v2
	v_mov_b32_e32 v126, v2
	v_mov_b32_e32 v127, v2
	v_mov_b32_e32 v128, v2
	v_mov_b32_e32 v129, v2
	v_mov_b32_e32 v142, v2
	v_mov_b32_e32 v143, v2
	v_mov_b32_e32 v144, v2
	v_mov_b32_e32 v145, v2
	v_mov_b32_e32 v138, v2
	v_mov_b32_e32 v139, v2
	v_mov_b32_e32 v140, v2
	v_mov_b32_e32 v141, v2

.LBB0_784:
	s_ashr_i32 s55, s54, 31
	s_lshl_b64 s[18:19], s[54:55], 19
	s_add_u32 s30, s16, s18
	s_addc_u32 s31, s17, s19
	s_ashr_i32 s63, s62, 31
	s_lshl_b64 s[18:19], s[62:63], 19
	s_add_u32 s34, s21, s18
	v_mov_b32_e32 v145, 0
	s_addc_u32 s35, s23, s19
	s_andn2_b64 vcc, exec, s[56:57]
	s_cbranch_vccnz .LBB0_788
	s_and_b64 s[18:19], s[40:41], exec
	s_cselect_b32 s1, s31, s37
	s_cselect_b32 s42, s30, s36
	s_cselect_b32 s43, s35, s27
	s_cselect_b32 s44, s34, s26
	s_add_u32 s45, s36, 0x100
	s_addc_u32 s55, s37, 0
	s_add_u32 s63, s26, 0x100
	v_mov_b32_e32 v2, 0
	s_addc_u32 s81, s27, 0
	s_mov_b32 s18, 0
	v_mov_b32_e32 v3, v2
	v_mov_b32_e32 v4, v2
	v_mov_b32_e32 v5, v2
	v_mov_b32_e32 v6, v2
	v_mov_b32_e32 v7, v2
	v_mov_b32_e32 v8, v2
	v_mov_b32_e32 v9, v2
	v_mov_b32_e32 v18, v2
	v_mov_b32_e32 v19, v2
	v_mov_b32_e32 v20, v2
	v_mov_b32_e32 v21, v2
	v_mov_b32_e32 v22, v2
	v_mov_b32_e32 v23, v2
	v_mov_b32_e32 v24, v2
	v_mov_b32_e32 v25, v2
	v_mov_b32_e32 v34, v2
	v_mov_b32_e32 v35, v2
	v_mov_b32_e32 v36, v2
	v_mov_b32_e32 v37, v2
	v_mov_b32_e32 v38, v2
	v_mov_b32_e32 v39, v2
	v_mov_b32_e32 v40, v2
	v_mov_b32_e32 v41, v2
	v_mov_b32_e32 v50, v2
	v_mov_b32_e32 v51, v2
	v_mov_b32_e32 v52, v2
	v_mov_b32_e32 v53, v2
	v_mov_b32_e32 v54, v2
	v_mov_b32_e32 v55, v2
	v_mov_b32_e32 v56, v2
	v_mov_b32_e32 v57, v2
	v_mov_b32_e32 v10, v2
	v_mov_b32_e32 v11, v2
	v_mov_b32_e32 v12, v2
	v_mov_b32_e32 v13, v2
	v_mov_b32_e32 v14, v2
	v_mov_b32_e32 v15, v2
	v_mov_b32_e32 v16, v2
	v_mov_b32_e32 v17, v2
	v_mov_b32_e32 v26, v2
	v_mov_b32_e32 v27, v2
	v_mov_b32_e32 v28, v2
	v_mov_b32_e32 v29, v2
	v_mov_b32_e32 v30, v2
	v_mov_b32_e32 v31, v2
	v_mov_b32_e32 v32, v2
	v_mov_b32_e32 v33, v2
	v_mov_b32_e32 v42, v2
	v_mov_b32_e32 v43, v2
	v_mov_b32_e32 v44, v2
	v_mov_b32_e32 v45, v2
	v_mov_b32_e32 v46, v2
	v_mov_b32_e32 v47, v2
	v_mov_b32_e32 v48, v2
	v_mov_b32_e32 v49, v2
	v_mov_b32_e32 v62, v2
	v_mov_b32_e32 v63, v2
	v_mov_b32_e32 v64, v2
	v_mov_b32_e32 v65, v2
	v_mov_b32_e32 v70, v2
	v_mov_b32_e32 v71, v2
	v_mov_b32_e32 v72, v2
	v_mov_b32_e32 v73, v2
	v_mov_b32_e32 v82, v2
	v_mov_b32_e32 v83, v2
	v_mov_b32_e32 v84, v2
	v_mov_b32_e32 v85, v2
	v_mov_b32_e32 v86, v2
	v_mov_b32_e32 v87, v2
	v_mov_b32_e32 v88, v2
	v_mov_b32_e32 v89, v2
	v_mov_b32_e32 v98, v2
	v_mov_b32_e32 v99, v2
	v_mov_b32_e32 v100, v2
	v_mov_b32_e32 v101, v2
	v_mov_b32_e32 v102, v2
	v_mov_b32_e32 v103, v2
	v_mov_b32_e32 v104, v2
	v_mov_b32_e32 v105, v2
	v_mov_b32_e32 v114, v2
	v_mov_b32_e32 v115, v2
	v_mov_b32_e32 v116, v2
	v_mov_b32_e32 v117, v2
	v_mov_b32_e32 v118, v2
	v_mov_b32_e32 v119, v2
	v_mov_b32_e32 v120, v2
	v_mov_b32_e32 v121, v2
	v_mov_b32_e32 v130, v2
	v_mov_b32_e32 v131, v2
	v_mov_b32_e32 v132, v2
	v_mov_b32_e32 v133, v2
	v_mov_b32_e32 v134, v2
	v_mov_b32_e32 v135, v2
	v_mov_b32_e32 v136, v2
	v_mov_b32_e32 v137, v2
	v_mov_b32_e32 v90, v2
	v_mov_b32_e32 v91, v2
	v_mov_b32_e32 v92, v2
	v_mov_b32_e32 v93, v2
	v_mov_b32_e32 v94, v2
	v_mov_b32_e32 v95, v2
	v_mov_b32_e32 v96, v2
	v_mov_b32_e32 v97, v2
	v_mov_b32_e32 v106, v2
	v_mov_b32_e32 v107, v2
	v_mov_b32_e32 v108, v2
	v_mov_b32_e32 v109, v2
	v_mov_b32_e32 v110, v2
	v_mov_b32_e32 v111, v2
	v_mov_b32_e32 v112, v2
	v_mov_b32_e32 v113, v2
	v_mov_b32_e32 v122, v2
	v_mov_b32_e32 v123, v2
	v_mov_b32_e32 v124, v2
	v_mov_b32_e32 v125, v2
	v_mov_b32_e32 v126, v2
	v_mov_b32_e32 v127, v2
	v_mov_b32_e32 v128, v2
	v_mov_b32_e32 v129, v2
	v_mov_b32_e32 v138, v2
	v_mov_b32_e32 v139, v2
	v_mov_b32_e32 v140, v2
	v_mov_b32_e32 v141, v2
	v_mov_b32_e32 v142, v2
	v_mov_b32_e32 v143, v2
	v_mov_b32_e32 v144, v2
	v_mov_b32_e32 v145, v2

.LBB0_996:
	s_ashr_i32 s56, s50, 1
	s_ashr_i32 s63, s62, 31
	s_ashr_i32 s57, s56, 31
	s_lshl_b64 s[18:19], s[62:63], 19
	s_lshl_b64 s[56:57], s[56:57], 8
	s_add_u32 s18, s42, s18
	s_addc_u32 s19, s43, s19
	s_add_u32 s60, s18, s56
	s_addc_u32 s61, s19, s57
	s_ashr_i32 s51, s50, 31
	s_lshl_b64 s[18:19], s[50:51], 16
	s_add_u32 s56, s23, s18
	v_mov_b32_e32 v157, 0
	s_addc_u32 s57, s36, s19
	s_andn2_b64 vcc, exec, s[46:47]
	s_cbranch_vccnz .LBB0_1000
	s_and_b64 s[18:19], s[40:41], exec
	s_cselect_b32 s51, s61, s27
	s_cselect_b32 s63, s60, s26
	s_cselect_b32 s78, s57, s3
	s_cselect_b32 s79, s56, s2
	s_add_u32 s80, s26, 0x100
	s_addc_u32 s81, s27, 0
	s_add_u32 s82, s2, 0x100
	v_mov_b32_e32 v2, 0
	s_addc_u32 s83, s3, 0
	s_mov_b32 s2, 0
	v_mov_b32_e32 v3, v2
	v_mov_b32_e32 v4, v2
	v_mov_b32_e32 v5, v2
	v_mov_b32_e32 v78, v2
	v_mov_b32_e32 v79, v2
	v_mov_b32_e32 v80, v2
	v_mov_b32_e32 v81, v2
	v_mov_b32_e32 v10, v2
	v_mov_b32_e32 v11, v2
	v_mov_b32_e32 v12, v2
	v_mov_b32_e32 v13, v2
	v_mov_b32_e32 v90, v2
	v_mov_b32_e32 v91, v2
	v_mov_b32_e32 v92, v2
	v_mov_b32_e32 v93, v2
	v_mov_b32_e32 v18, v2
	v_mov_b32_e32 v19, v2
	v_mov_b32_e32 v20, v2
	v_mov_b32_e32 v21, v2
	v_mov_b32_e32 v102, v2
	v_mov_b32_e32 v103, v2
	v_mov_b32_e32 v104, v2
	v_mov_b32_e32 v105, v2
	v_mov_b32_e32 v26, v2
	v_mov_b32_e32 v27, v2
	v_mov_b32_e32 v28, v2
	v_mov_b32_e32 v29, v2
	v_mov_b32_e32 v114, v2
	v_mov_b32_e32 v115, v2
	v_mov_b32_e32 v116, v2
	v_mov_b32_e32 v117, v2
	v_mov_b32_e32 v6, v2
	v_mov_b32_e32 v7, v2
	v_mov_b32_e32 v8, v2
	v_mov_b32_e32 v9, v2
	v_mov_b32_e32 v82, v2
	v_mov_b32_e32 v83, v2
	v_mov_b32_e32 v84, v2
	v_mov_b32_e32 v85, v2
	v_mov_b32_e32 v14, v2
	v_mov_b32_e32 v15, v2
	v_mov_b32_e32 v16, v2
	v_mov_b32_e32 v17, v2
	v_mov_b32_e32 v94, v2
	v_mov_b32_e32 v95, v2
	v_mov_b32_e32 v96, v2
	v_mov_b32_e32 v97, v2
	v_mov_b32_e32 v22, v2
	v_mov_b32_e32 v23, v2
	v_mov_b32_e32 v24, v2
	v_mov_b32_e32 v25, v2
	v_mov_b32_e32 v106, v2
	v_mov_b32_e32 v107, v2
	v_mov_b32_e32 v108, v2
	v_mov_b32_e32 v109, v2
	v_mov_b32_e32 v30, v2
	v_mov_b32_e32 v31, v2
	v_mov_b32_e32 v32, v2
	v_mov_b32_e32 v33, v2
	v_mov_b32_e32 v118, v2
	v_mov_b32_e32 v119, v2
	v_mov_b32_e32 v120, v2
	v_mov_b32_e32 v121, v2
	v_mov_b32_e32 v34, v2
	v_mov_b32_e32 v35, v2
	v_mov_b32_e32 v36, v2
	v_mov_b32_e32 v37, v2
	v_mov_b32_e32 v126, v2
	v_mov_b32_e32 v127, v2
	v_mov_b32_e32 v128, v2
	v_mov_b32_e32 v129, v2
	v_mov_b32_e32 v42, v2
	v_mov_b32_e32 v43, v2
	v_mov_b32_e32 v44, v2
	v_mov_b32_e32 v45, v2
	v_mov_b32_e32 v134, v2
	v_mov_b32_e32 v135, v2
	v_mov_b32_e32 v136, v2
	v_mov_b32_e32 v137, v2
	v_mov_b32_e32 v50, v2
	v_mov_b32_e32 v51, v2
	v_mov_b32_e32 v52, v2
	v_mov_b32_e32 v53, v2
	v_mov_b32_e32 v142, v2
	v_mov_b32_e32 v143, v2
	v_mov_b32_e32 v144, v2
	v_mov_b32_e32 v145, v2
	v_mov_b32_e32 v58, v2
	v_mov_b32_e32 v59, v2
	v_mov_b32_e32 v60, v2
	v_mov_b32_e32 v61, v2
	v_mov_b32_e32 v150, v2
	v_mov_b32_e32 v151, v2
	v_mov_b32_e32 v152, v2
	v_mov_b32_e32 v153, v2
	v_mov_b32_e32 v38, v2
	v_mov_b32_e32 v39, v2
	v_mov_b32_e32 v40, v2
	v_mov_b32_e32 v41, v2
	v_mov_b32_e32 v130, v2
	v_mov_b32_e32 v131, v2
	v_mov_b32_e32 v132, v2
	v_mov_b32_e32 v133, v2
	v_mov_b32_e32 v46, v2
	v_mov_b32_e32 v47, v2
	v_mov_b32_e32 v48, v2
	v_mov_b32_e32 v49, v2
	v_mov_b32_e32 v138, v2
	v_mov_b32_e32 v139, v2
	v_mov_b32_e32 v140, v2
	v_mov_b32_e32 v141, v2
	v_mov_b32_e32 v54, v2
	v_mov_b32_e32 v55, v2
	v_mov_b32_e32 v56, v2
	v_mov_b32_e32 v57, v2
	v_mov_b32_e32 v146, v2
	v_mov_b32_e32 v147, v2
	v_mov_b32_e32 v148, v2
	v_mov_b32_e32 v149, v2
	v_mov_b32_e32 v62, v2
	v_mov_b32_e32 v63, v2
	v_mov_b32_e32 v64, v2
	v_mov_b32_e32 v65, v2
	v_mov_b32_e32 v154, v2
	v_mov_b32_e32 v155, v2
	v_mov_b32_e32 v156, v2
	v_mov_b32_e32 v157, v2

.LBB0_1313:
	s_ashr_i32 s55, s54, 31
	s_lshl_b64 s[18:19], s[54:55], 19
	s_add_u32 s56, s17, s18
	s_addc_u32 s57, s21, s19
	s_ashr_i32 s37, s36, 31
	s_lshl_b64 s[18:19], s[36:37], 19
	s_add_u32 s60, s22, s18
	v_mov_b32_e32 v141, 0
	s_addc_u32 s61, s23, s19
	s_andn2_b64 vcc, exec, s[46:47]
	s_waitcnt lgkmcnt(0)
	s_cbranch_vccnz .LBB0_1317
	s_and_b64 s[18:19], s[40:41], exec
	s_cselect_b32 s1, s57, s27
	s_cselect_b32 s37, s56, s26
	s_cselect_b32 s55, s61, s3
	s_cselect_b32 s89, s60, s2
	s_add_u32 vcc_lo, s26, 0x100
	s_addc_u32 vcc_hi, s27, 0
	s_add_u32 s90, s2, 0x100
	s_addc_u32 s91, s3, 0
	s_add_u32 s94, s26, 0x40080
	v_mov_b32_e32 v2, 0
	s_addc_u32 s95, s27, 0
	s_mov_b32 s18, 0
	v_mov_b32_e32 v3, v2
	v_mov_b32_e32 v4, v2
	v_mov_b32_e32 v5, v2
	v_mov_b32_e32 v6, v2
	v_mov_b32_e32 v7, v2
	v_mov_b32_e32 v8, v2
	v_mov_b32_e32 v9, v2
	v_mov_b32_e32 v18, v2
	v_mov_b32_e32 v19, v2
	v_mov_b32_e32 v20, v2
	v_mov_b32_e32 v21, v2
	v_mov_b32_e32 v22, v2
	v_mov_b32_e32 v23, v2
	v_mov_b32_e32 v24, v2
	v_mov_b32_e32 v25, v2
	v_mov_b32_e32 v34, v2
	v_mov_b32_e32 v35, v2
	v_mov_b32_e32 v36, v2
	v_mov_b32_e32 v37, v2
	v_mov_b32_e32 v38, v2
	v_mov_b32_e32 v39, v2
	v_mov_b32_e32 v40, v2
	v_mov_b32_e32 v41, v2
	v_mov_b32_e32 v50, v2
	v_mov_b32_e32 v51, v2
	v_mov_b32_e32 v52, v2
	v_mov_b32_e32 v53, v2
	v_mov_b32_e32 v54, v2
	v_mov_b32_e32 v55, v2
	v_mov_b32_e32 v56, v2
	v_mov_b32_e32 v57, v2
	v_mov_b32_e32 v10, v2
	v_mov_b32_e32 v11, v2
	v_mov_b32_e32 v12, v2
	v_mov_b32_e32 v13, v2
	v_mov_b32_e32 v14, v2
	v_mov_b32_e32 v15, v2
	v_mov_b32_e32 v16, v2
	v_mov_b32_e32 v17, v2
	v_mov_b32_e32 v26, v2
	v_mov_b32_e32 v27, v2
	v_mov_b32_e32 v28, v2
	v_mov_b32_e32 v29, v2
	v_mov_b32_e32 v30, v2
	v_mov_b32_e32 v31, v2
	v_mov_b32_e32 v32, v2
	v_mov_b32_e32 v33, v2
	v_mov_b32_e32 v42, v2
	v_mov_b32_e32 v43, v2
	v_mov_b32_e32 v44, v2
	v_mov_b32_e32 v45, v2
	v_mov_b32_e32 v46, v2
	v_mov_b32_e32 v47, v2
	v_mov_b32_e32 v48, v2
	v_mov_b32_e32 v49, v2
	v_mov_b32_e32 v58, v2
	v_mov_b32_e32 v59, v2
	v_mov_b32_e32 v60, v2
	v_mov_b32_e32 v61, v2
	v_mov_b32_e32 v62, v2
	v_mov_b32_e32 v63, v2
	v_mov_b32_e32 v64, v2
	v_mov_b32_e32 v65, v2
	v_mov_b32_e32 v82, v2
	v_mov_b32_e32 v83, v2
	v_mov_b32_e32 v84, v2
	v_mov_b32_e32 v85, v2
	v_mov_b32_e32 v86, v2
	v_mov_b32_e32 v87, v2
	v_mov_b32_e32 v88, v2
	v_mov_b32_e32 v89, v2
	v_mov_b32_e32 v98, v2
	v_mov_b32_e32 v99, v2
	v_mov_b32_e32 v100, v2
	v_mov_b32_e32 v101, v2
	v_mov_b32_e32 v102, v2
	v_mov_b32_e32 v103, v2
	v_mov_b32_e32 v104, v2
	v_mov_b32_e32 v105, v2
	v_mov_b32_e32 v114, v2
	v_mov_b32_e32 v115, v2
	v_mov_b32_e32 v116, v2
	v_mov_b32_e32 v117, v2
	v_mov_b32_e32 v118, v2
	v_mov_b32_e32 v119, v2
	v_mov_b32_e32 v120, v2
	v_mov_b32_e32 v121, v2
	v_mov_b32_e32 v130, v2
	v_mov_b32_e32 v131, v2
	v_mov_b32_e32 v132, v2
	v_mov_b32_e32 v133, v2
	v_mov_b32_e32 v134, v2
	v_mov_b32_e32 v135, v2
	v_mov_b32_e32 v136, v2
	v_mov_b32_e32 v137, v2
	v_mov_b32_e32 v90, v2
	v_mov_b32_e32 v91, v2
	v_mov_b32_e32 v92, v2
	v_mov_b32_e32 v93, v2
	v_mov_b32_e32 v94, v2
	v_mov_b32_e32 v95, v2
	v_mov_b32_e32 v96, v2
	v_mov_b32_e32 v97, v2
	v_mov_b32_e32 v106, v2
	v_mov_b32_e32 v107, v2
	v_mov_b32_e32 v108, v2
	v_mov_b32_e32 v109, v2
	v_mov_b32_e32 v110, v2
	v_mov_b32_e32 v111, v2
	v_mov_b32_e32 v112, v2
	v_mov_b32_e32 v113, v2
	v_mov_b32_e32 v122, v2
	v_mov_b32_e32 v123, v2
	v_mov_b32_e32 v124, v2
	v_mov_b32_e32 v125, v2
	v_mov_b32_e32 v126, v2
	v_mov_b32_e32 v127, v2
	v_mov_b32_e32 v128, v2
	v_mov_b32_e32 v129, v2
	v_mov_b32_e32 v142, v2
	v_mov_b32_e32 v143, v2
	v_mov_b32_e32 v144, v2
	v_mov_b32_e32 v145, v2
	v_mov_b32_e32 v138, v2
	v_mov_b32_e32 v139, v2
	v_mov_b32_e32 v140, v2
	v_mov_b32_e32 v141, v2

.LBB0_1403:
	s_ashr_i32 s47, s46, 31
	s_lshl_b64 s[18:19], s[46:47], 19
	s_add_u32 s48, s17, s18
	s_addc_u32 s49, s21, s19
	s_ashr_i32 s45, s44, 31
	s_lshl_b64 s[18:19], s[44:45], 19
	s_add_u32 s50, s25, s18
	v_mov_b32_e32 v125, 0
	s_addc_u32 s51, s39, s19
	s_andn2_b64 vcc, exec, s[34:35]
	s_cbranch_vccnz .LBB0_1407
	s_and_b64 s[18:19], s[40:41], exec
	s_cselect_b32 s45, s49, s55
	s_cselect_b32 s47, s48, s54
	s_cselect_b32 s73, s51, s27
	s_cselect_b32 s78, s50, s26
	s_add_u32 s79, s54, 0x100
	s_addc_u32 s80, s55, 0
	s_add_u32 s81, s26, 0x100
	v_mov_b32_e32 v6, 0
	s_addc_u32 s82, s27, 0
	s_mov_b32 s18, 0
	v_mov_b32_e32 v7, v6
	v_mov_b32_e32 v8, v6
	v_mov_b32_e32 v9, v6
	v_mov_b32_e32 v2, v6
	v_mov_b32_e32 v3, v6
	v_mov_b32_e32 v4, v6
	v_mov_b32_e32 v5, v6
	v_mov_b32_e32 v22, v6
	v_mov_b32_e32 v23, v6
	v_mov_b32_e32 v24, v6
	v_mov_b32_e32 v25, v6
	v_mov_b32_e32 v18, v6
	v_mov_b32_e32 v19, v6
	v_mov_b32_e32 v20, v6
	v_mov_b32_e32 v21, v6
	v_mov_b32_e32 v38, v6
	v_mov_b32_e32 v39, v6
	v_mov_b32_e32 v40, v6
	v_mov_b32_e32 v41, v6
	v_mov_b32_e32 v34, v6
	v_mov_b32_e32 v35, v6
	v_mov_b32_e32 v36, v6
	v_mov_b32_e32 v37, v6
	v_mov_b32_e32 v54, v6
	v_mov_b32_e32 v55, v6
	v_mov_b32_e32 v56, v6
	v_mov_b32_e32 v57, v6
	v_mov_b32_e32 v50, v6
	v_mov_b32_e32 v51, v6
	v_mov_b32_e32 v52, v6
	v_mov_b32_e32 v53, v6
	v_mov_b32_e32 v14, v6
	v_mov_b32_e32 v15, v6
	v_mov_b32_e32 v16, v6
	v_mov_b32_e32 v17, v6
	v_mov_b32_e32 v10, v6
	v_mov_b32_e32 v11, v6
	v_mov_b32_e32 v12, v6
	v_mov_b32_e32 v13, v6
	v_mov_b32_e32 v30, v6
	v_mov_b32_e32 v31, v6
	v_mov_b32_e32 v32, v6
	v_mov_b32_e32 v33, v6
	v_mov_b32_e32 v26, v6
	v_mov_b32_e32 v27, v6
	v_mov_b32_e32 v28, v6
	v_mov_b32_e32 v29, v6
	v_mov_b32_e32 v46, v6
	v_mov_b32_e32 v47, v6
	v_mov_b32_e32 v48, v6
	v_mov_b32_e32 v49, v6
	v_mov_b32_e32 v42, v6
	v_mov_b32_e32 v43, v6
	v_mov_b32_e32 v44, v6
	v_mov_b32_e32 v45, v6
	v_mov_b32_e32 v62, v6
	v_mov_b32_e32 v63, v6
	v_mov_b32_e32 v64, v6
	v_mov_b32_e32 v65, v6
	v_mov_b32_e32 v58, v6
	v_mov_b32_e32 v59, v6
	v_mov_b32_e32 v60, v6
	v_mov_b32_e32 v61, v6
	v_mov_b32_e32 v70, v6
	v_mov_b32_e32 v71, v6
	v_mov_b32_e32 v72, v6
	v_mov_b32_e32 v73, v6
	v_mov_b32_e32 v66, v6
	v_mov_b32_e32 v67, v6
	v_mov_b32_e32 v68, v6
	v_mov_b32_e32 v69, v6
	v_mov_b32_e32 v86, v6
	v_mov_b32_e32 v87, v6
	v_mov_b32_e32 v88, v6
	v_mov_b32_e32 v89, v6
	v_mov_b32_e32 v82, v6
	v_mov_b32_e32 v83, v6
	v_mov_b32_e32 v84, v6
	v_mov_b32_e32 v85, v6
	v_mov_b32_e32 v102, v6
	v_mov_b32_e32 v103, v6
	v_mov_b32_e32 v104, v6
	v_mov_b32_e32 v105, v6
	v_mov_b32_e32 v98, v6
	v_mov_b32_e32 v99, v6
	v_mov_b32_e32 v100, v6
	v_mov_b32_e32 v101, v6
	v_mov_b32_e32 v118, v6
	v_mov_b32_e32 v119, v6
	v_mov_b32_e32 v120, v6
	v_mov_b32_e32 v121, v6
	v_mov_b32_e32 v114, v6
	v_mov_b32_e32 v115, v6
	v_mov_b32_e32 v116, v6
	v_mov_b32_e32 v117, v6
	v_mov_b32_e32 v78, v6
	v_mov_b32_e32 v79, v6
	v_mov_b32_e32 v80, v6
	v_mov_b32_e32 v81, v6
	v_mov_b32_e32 v74, v6
	v_mov_b32_e32 v75, v6
	v_mov_b32_e32 v76, v6
	v_mov_b32_e32 v77, v6
	v_mov_b32_e32 v94, v6
	v_mov_b32_e32 v95, v6
	v_mov_b32_e32 v96, v6
	v_mov_b32_e32 v97, v6
	v_mov_b32_e32 v90, v6
	v_mov_b32_e32 v91, v6
	v_mov_b32_e32 v92, v6
	v_mov_b32_e32 v93, v6
	v_mov_b32_e32 v110, v6
	v_mov_b32_e32 v111, v6
	v_mov_b32_e32 v112, v6
	v_mov_b32_e32 v113, v6
	v_mov_b32_e32 v106, v6
	v_mov_b32_e32 v107, v6
	v_mov_b32_e32 v108, v6
	v_mov_b32_e32 v109, v6
	v_mov_b32_e32 v126, v6
	v_mov_b32_e32 v127, v6
	v_mov_b32_e32 v128, v6
	v_mov_b32_e32 v129, v6
	v_mov_b32_e32 v122, v6
	v_mov_b32_e32 v123, v6
	v_mov_b32_e32 v124, v6
	v_mov_b32_e32 v125, v6

.LBB0_1492:
	s_ashr_i32 s73, s72, 31
	s_lshl_b64 s[0:1], s[72:73], 21
	s_add_u32 s2, s16, s0
	s_addc_u32 s3, s17, s1
	s_ashr_i32 s61, s60, 31
	s_lshl_b64 s[0:1], s[60:61], 21
	s_add_u32 s0, s21, s0
	v_mov_b32_e32 v141, 0
	s_addc_u32 s1, s22, s1
	s_andn2_b64 vcc, exec, s[54:55]
	s_waitcnt lgkmcnt(0)
	s_cbranch_vccnz .LBB0_1496
	s_and_b64 s[18:19], s[40:41], exec
	s_cselect_b32 s61, s3, s43
	s_cselect_b32 s73, s2, s42
	s_cselect_b32 s89, s1, s27
	s_cselect_b32 vcc_lo, s0, s26
	s_add_u32 vcc_hi, s42, 0x100
	s_addc_u32 s90, s43, 0
	s_add_u32 s91, s26, 0x100
	s_addc_u32 s92, s27, 0
	s_add_u32 s42, s42, 0x100080
	v_mov_b32_e32 v2, 0
	s_mov_b32 s24, s66
	s_mov_b32 s66, s97
	s_addc_u32 s43, s43, 0
	s_mov_b32 s18, 0
	v_mov_b32_e32 v3, v2
	v_mov_b32_e32 v4, v2
	v_mov_b32_e32 v5, v2
	v_mov_b32_e32 v6, v2
	v_mov_b32_e32 v7, v2
	v_mov_b32_e32 v8, v2
	v_mov_b32_e32 v9, v2
	v_mov_b32_e32 v18, v2
	v_mov_b32_e32 v19, v2
	v_mov_b32_e32 v20, v2
	v_mov_b32_e32 v21, v2
	v_mov_b32_e32 v22, v2
	v_mov_b32_e32 v23, v2
	v_mov_b32_e32 v24, v2
	v_mov_b32_e32 v25, v2
	v_mov_b32_e32 v34, v2
	v_mov_b32_e32 v35, v2
	v_mov_b32_e32 v36, v2
	v_mov_b32_e32 v37, v2
	v_mov_b32_e32 v38, v2
	v_mov_b32_e32 v39, v2
	v_mov_b32_e32 v40, v2
	v_mov_b32_e32 v41, v2
	v_mov_b32_e32 v50, v2
	v_mov_b32_e32 v51, v2
	v_mov_b32_e32 v52, v2
	v_mov_b32_e32 v53, v2
	v_mov_b32_e32 v54, v2
	v_mov_b32_e32 v55, v2
	v_mov_b32_e32 v56, v2
	v_mov_b32_e32 v57, v2
	v_mov_b32_e32 v10, v2
	v_mov_b32_e32 v11, v2
	v_mov_b32_e32 v12, v2
	v_mov_b32_e32 v13, v2
	v_mov_b32_e32 v14, v2
	v_mov_b32_e32 v15, v2
	v_mov_b32_e32 v16, v2
	v_mov_b32_e32 v17, v2
	v_mov_b32_e32 v26, v2
	v_mov_b32_e32 v27, v2
	v_mov_b32_e32 v28, v2
	v_mov_b32_e32 v29, v2
	v_mov_b32_e32 v30, v2
	v_mov_b32_e32 v31, v2
	v_mov_b32_e32 v32, v2
	v_mov_b32_e32 v33, v2
	v_mov_b32_e32 v42, v2
	v_mov_b32_e32 v43, v2
	v_mov_b32_e32 v44, v2
	v_mov_b32_e32 v45, v2
	v_mov_b32_e32 v46, v2
	v_mov_b32_e32 v47, v2
	v_mov_b32_e32 v48, v2
	v_mov_b32_e32 v49, v2
	v_mov_b32_e32 v58, v2
	v_mov_b32_e32 v59, v2
	v_mov_b32_e32 v60, v2
	v_mov_b32_e32 v61, v2
	v_mov_b32_e32 v62, v2
	v_mov_b32_e32 v63, v2
	v_mov_b32_e32 v64, v2
	v_mov_b32_e32 v65, v2
	v_mov_b32_e32 v66, v2
	v_mov_b32_e32 v67, v2
	v_mov_b32_e32 v68, v2
	v_mov_b32_e32 v69, v2
	v_mov_b32_e32 v70, v2
	v_mov_b32_e32 v71, v2
	v_mov_b32_e32 v72, v2
	v_mov_b32_e32 v73, v2
	v_mov_b32_e32 v86, v2
	v_mov_b32_e32 v87, v2
	v_mov_b32_e32 v88, v2
	v_mov_b32_e32 v89, v2
	v_mov_b32_e32 v94, v2
	v_mov_b32_e32 v95, v2
	v_mov_b32_e32 v96, v2
	v_mov_b32_e32 v97, v2
	v_mov_b32_e32 v114, v2
	v_mov_b32_e32 v115, v2
	v_mov_b32_e32 v116, v2
	v_mov_b32_e32 v117, v2
	v_mov_b32_e32 v118, v2
	v_mov_b32_e32 v119, v2
	v_mov_b32_e32 v120, v2
	v_mov_b32_e32 v121, v2
	v_mov_b32_e32 v130, v2
	v_mov_b32_e32 v131, v2
	v_mov_b32_e32 v132, v2
	v_mov_b32_e32 v133, v2
	v_mov_b32_e32 v134, v2
	v_mov_b32_e32 v135, v2
	v_mov_b32_e32 v136, v2
	v_mov_b32_e32 v137, v2
	v_mov_b32_e32 v74, v2
	v_mov_b32_e32 v75, v2
	v_mov_b32_e32 v76, v2
	v_mov_b32_e32 v77, v2
	v_mov_b32_e32 v78, v2
	v_mov_b32_e32 v79, v2
	v_mov_b32_e32 v80, v2
	v_mov_b32_e32 v81, v2
	v_mov_b32_e32 v102, v2
	v_mov_b32_e32 v103, v2
	v_mov_b32_e32 v104, v2
	v_mov_b32_e32 v105, v2
	v_mov_b32_e32 v106, v2
	v_mov_b32_e32 v107, v2
	v_mov_b32_e32 v108, v2
	v_mov_b32_e32 v109, v2
	v_mov_b32_e32 v122, v2
	v_mov_b32_e32 v123, v2
	v_mov_b32_e32 v124, v2
	v_mov_b32_e32 v125, v2
	v_mov_b32_e32 v126, v2
	v_mov_b32_e32 v127, v2
	v_mov_b32_e32 v128, v2
	v_mov_b32_e32 v129, v2
	v_mov_b32_e32 v142, v2
	v_mov_b32_e32 v143, v2
	v_mov_b32_e32 v144, v2
	v_mov_b32_e32 v145, v2
	v_mov_b32_e32 v138, v2
	v_mov_b32_e32 v139, v2
	v_mov_b32_e32 v140, v2
	v_mov_b32_e32 v141, v2
